# GEMM K-loops: priority inverted, the load-phase wave runs at prio 1 and the MFMA-phase wave at prio 0
# baseline (speedup 1.0000x reference)
; #define PG8_STAGE(bufoff, gbase, voff) do { _Pragma("unroll") for (int _i = 0; _i < 2; ++_i) \
;         __builtin_amdgcn_global_load_lds((const unsigned*)((const char*)(gbase) + (voff)[_i]), (PG8_LAS unsigned*)(lds + (bufoff) + ldsw + _i * 8192), 16, 0, 0); } while (0)
; #define PG8_LDA(dst, b, h) do { _Pragma("unroll") for (int m = 0; m < 4; ++m) _Pragma("unroll") for (int k = 0; k < 2; ++k) dst[m][k] = *(const PG8_LAS bf16x8*)(lds + PG8_SA(b, h) + aoff + m * 2048 + k * 1024); } while (0)
; #define PG8_LDB(dst, b, h) do { _Pragma("unroll") for (int n = 0; n < 2; ++n) _Pragma("unroll") for (int k = 0; k < 2; ++k) dst[n][k] = *(const PG8_LAS bf16x8*)(lds + PG8_SB(b, h) + boff + n * 2048 + k * 1024); } while (0)
; #define PG8_WAIT_V(n) asm volatile("s_waitcnt vmcnt(" #n ")" ::: "memory")
; #define PG8_WAIT_L(n) asm volatile("s_waitcnt lgkmcnt(" #n ")" ::: "memory")
; #define PG8_BAR __builtin_amdgcn_s_barrier()
; #define PG8_SCHED __builtin_amdgcn_sched_barrier(0)
; template <class Epi, class Sched, bool ALIGN_EPI = false, bool SP2 = false>
; __device__ __forceinline__ void gemm_phase(PG8_LAS unsigned char* lds, const Gemm g, const Sched& S, const Epi& E, int wave_in) {
;     ...
;         const char* nA = has_next ? (const char*)g.A + (size_t)nxt.pm * tstepA : cA; const char* nB = has_next ? (const char*)g.Bt + (size_t)nxt.pn * tstep : cB;
;         for (int t = 0; t < nt; t += 2) {
;             const bool last = (t == nt - 2);
;             const char* a1 = cA + (size_t)(t + 1) * kstep;
;             const char* a2 = last ? nA : cA + (size_t)(t + 2) * kstep; const char* b2 = last ? nB : cB + (size_t)(t + 2) * kstep;
;             const char* a3 = a2 + kstep; const char* b3 = b2 + kstep;
;             if (last && has_next) S.a_ready(nxt);
;             if constexpr (SP2) {
;             PG8_LDB(B0, 0, 0); PG8_LDB(B1, 0, 1); PG8_SCHED; PG8_LDA(At, 0, 0); PG8_STAGE(PG8_SA(1, 1), a1 + hstepA, voffA);
;             PG8_WAIT_V(8); PG8_WAIT_L(0); PG8_BAR; PG8_MMA(0, 0, At, B0); PG8_MMA(0, 1, At, B1); PG8_BAR; PG8_SCHED;
;             PG8_LDA(At, 0, 1); PG8_STAGE(PG8_SB(0, 0), b2, voffB); PG8_STAGE(PG8_SB(0, 1), b2 + hstep, voffB); PG8_STAGE(PG8_SA(0, 0), a2, voffA);
;             PG8_WAIT_V(8); PG8_WAIT_L(0); PG8_BAR; PG8_MMA(1, 0, At, B0); PG8_MMA(1, 1, At, B1); PG8_BAR; PG8_SCHED;
.LBB0_43:
	s_add_u32 s50, s48, 0xfff80080
	s_addc_u32 s51, s49, -1
	s_add_i32 s72, 0, 0x10000
	s_cmp_eq_u32 s71, 28
	s_cselect_b32 s53, s43, s51
	s_cselect_b32 s52, s67, s50
	s_cselect_b32 s51, s41, s70
	s_cselect_b32 s50, s68, s69
	s_add_i32 s74, 0, 0x14000
	v_add_u32_e32 v118, s72, v214
	v_add_u32_e32 v178, s74, v214
	ds_read_b128 v[106:109], v118
	ds_read_b128 v[110:113], v118 offset:1024
	ds_read_b128 v[114:117], v118 offset:2048
	ds_read_b128 v[118:121], v118 offset:3072
	ds_read_b128 v[122:125], v178
	ds_read_b128 v[126:129], v178 offset:1024
	ds_read_b128 v[130:133], v178 offset:2048
	ds_read_b128 v[178:181], v178 offset:3072
	v_lshl_add_u64 v[238:239], s[48:49], 0, v[174:175]
	s_add_i32 m0, s58, 0xc000
	ds_read_b128 v[182:185], v217
	ds_read_b128 v[186:189], v217 offset:1024
	ds_read_b128 v[190:193], v217 offset:2048
	ds_read_b128 v[218:221], v217 offset:3072
	ds_read_b128 v[222:225], v217 offset:4096
	ds_read_b128 v[226:229], v217 offset:5120
	ds_read_b128 v[230:233], v217 offset:6144
	ds_read_b128 v[234:237], v217 offset:7168
	global_load_lds_dwordx4 v[238:239], off
	v_lshl_add_u64 v[238:239], s[48:49], 0, v[176:177]
	s_add_i32 m0, s58, 0xe000
	s_nop 0
	global_load_lds_dwordx4 v[238:239], off
	s_waitcnt vmcnt(8)
	s_waitcnt lgkmcnt(0)
	s_barrier
	s_setprio 0
	s_waitcnt lgkmcnt(0)
	v_mfma_f32_16x16x32_bf16 v[154:157], v[106:109], v[182:185], v[154:157]
	v_mfma_f32_16x16x32_bf16 v[62:65], v[114:117], v[182:185], v[62:65]
	v_mfma_f32_16x16x32_bf16 v[150:153], v[106:109], v[190:193], v[150:153]
	v_mfma_f32_16x16x32_bf16 v[54:57], v[114:117], v[190:193], v[54:57]
	v_mfma_f32_16x16x32_bf16 v[142:145], v[106:109], v[222:225], v[142:145]
	v_mfma_f32_16x16x32_bf16 v[46:49], v[114:117], v[222:225], v[46:49]
	v_mfma_f32_16x16x32_bf16 v[102:105], v[106:109], v[230:233], v[102:105]
	v_mfma_f32_16x16x32_bf16 v[38:41], v[114:117], v[230:233], v[38:41]
	v_mfma_f32_16x16x32_bf16 v[154:157], v[110:113], v[186:189], v[154:157]
	v_mfma_f32_16x16x32_bf16 v[62:65], v[118:121], v[186:189], v[62:65]
	v_mfma_f32_16x16x32_bf16 v[150:153], v[110:113], v[218:221], v[150:153]
	v_mfma_f32_16x16x32_bf16 v[54:57], v[118:121], v[218:221], v[54:57]
	v_mfma_f32_16x16x32_bf16 v[142:145], v[110:113], v[226:229], v[142:145]
	v_mfma_f32_16x16x32_bf16 v[46:49], v[118:121], v[226:229], v[46:49]
	v_mfma_f32_16x16x32_bf16 v[102:105], v[110:113], v[234:237], v[102:105]
	v_mfma_f32_16x16x32_bf16 v[38:41], v[118:121], v[234:237], v[38:41]
	v_mfma_f32_16x16x32_bf16 v[134:137], v[122:125], v[182:185], v[134:137]
	v_mfma_f32_16x16x32_bf16 v[58:61], v[130:133], v[182:185], v[58:61]
	v_mfma_f32_16x16x32_bf16 v[146:149], v[122:125], v[190:193], v[146:149]
	v_mfma_f32_16x16x32_bf16 v[50:53], v[130:133], v[190:193], v[50:53]
	v_mfma_f32_16x16x32_bf16 v[138:141], v[122:125], v[222:225], v[138:141]
	v_mfma_f32_16x16x32_bf16 v[42:45], v[130:133], v[222:225], v[42:45]
	v_mfma_f32_16x16x32_bf16 v[98:101], v[122:125], v[230:233], v[98:101]
	v_mfma_f32_16x16x32_bf16 v[34:37], v[130:133], v[230:233], v[34:37]
	v_mfma_f32_16x16x32_bf16 v[134:137], v[126:129], v[186:189], v[134:137]
	v_mfma_f32_16x16x32_bf16 v[58:61], v[178:181], v[186:189], v[58:61]
	v_mfma_f32_16x16x32_bf16 v[146:149], v[126:129], v[218:221], v[146:149]
	v_mfma_f32_16x16x32_bf16 v[50:53], v[178:181], v[218:221], v[50:53]
	v_mfma_f32_16x16x32_bf16 v[138:141], v[126:129], v[226:229], v[138:141]
	v_mfma_f32_16x16x32_bf16 v[42:45], v[178:181], v[226:229], v[42:45]
	v_mfma_f32_16x16x32_bf16 v[98:101], v[126:129], v[234:237], v[98:101]
	v_mfma_f32_16x16x32_bf16 v[34:37], v[178:181], v[234:237], v[34:37]
	s_setprio 1
	s_barrier
	s_add_i32 s72, s72, s57
	v_lshl_add_u64 v[238:239], s[50:51], 0, v[0:1]
	s_mov_b32 m0, s72
	ds_read_b128 v[182:185], v217 offset:16384
	ds_read_b128 v[186:189], v217 offset:17408
	ds_read_b128 v[190:193], v217 offset:18432
	ds_read_b128 v[218:221], v217 offset:19456
	ds_read_b128 v[222:225], v217 offset:20480
	ds_read_b128 v[226:229], v217 offset:21504
	ds_read_b128 v[230:233], v217 offset:22528
	ds_read_b128 v[234:237], v217 offset:23552
	global_load_lds_dwordx4 v[238:239], off
	s_add_i32 m0, s72, 0x2000
	s_add_u32 s72, s50, 0x80000
	v_lshl_add_u64 v[240:241], s[50:51], 0, v[168:169]
	s_addc_u32 s73, s51, 0
	s_add_i32 s74, s74, s57
	global_load_lds_dwordx4 v[240:241], off
	v_lshl_add_u64 v[242:243], s[72:73], 0, v[0:1]
	s_mov_b32 m0, s74
	v_lshl_add_u64 v[244:245], s[52:53], 0, v[170:171]
	global_load_lds_dwordx4 v[242:243], off
	v_lshl_add_u64 v[242:243], s[72:73], 0, v[168:169]
	s_add_i32 m0, s74, 0x2000
	s_nop 0
	global_load_lds_dwordx4 v[242:243], off
	v_lshl_add_u64 v[242:243], s[52:53], 0, v[172:173]
	s_mov_b32 m0, s58
	s_nop 0
	global_load_lds_dwordx4 v[242:243], off
	s_mov_b32 m0, s59
	s_nop 0
	global_load_lds_dwordx4 v[244:245], off
	s_waitcnt vmcnt(8)
	s_waitcnt lgkmcnt(0)
	s_barrier
; #define PG8_STAGE(bufoff, gbase, voff) do { _Pragma("unroll") for (int _i = 0; _i < 2; ++_i) \
;         __builtin_amdgcn_global_load_lds((const unsigned*)((const char*)(gbase) + (voff)[_i]), (PG8_LAS unsigned*)(lds + (bufoff) + ldsw + _i * 8192), 16, 0, 0); } while (0)
; #define PG8_LDA(dst, b, h) do { _Pragma("unroll") for (int m = 0; m < 4; ++m) _Pragma("unroll") for (int k = 0; k < 2; ++k) dst[m][k] = *(const PG8_LAS bf16x8*)(lds + PG8_SA(b, h) + aoff + m * 2048 + k * 1024); } while (0)
; #define PG8_LDB(dst, b, h) do { _Pragma("unroll") for (int n = 0; n < 2; ++n) _Pragma("unroll") for (int k = 0; k < 2; ++k) dst[n][k] = *(const PG8_LAS bf16x8*)(lds + PG8_SB(b, h) + boff + n * 2048 + k * 1024); } while (0)
; #define PG8_MMA(ai, bj, At, Bt) do { __builtin_amdgcn_s_setprio(1); _Pragma("unroll") for (int m = 0; m < 4; ++m) _Pragma("unroll") for (int n = 0; n < 2; ++n) _Pragma("unroll") for (int k = 0; k < 2; ++k) \
;         acc[ai][bj][m][n] = __builtin_amdgcn_mfma_f32_16x16x32_bf16(Bt[n][k], At[m][k], acc[ai][bj][m][n], 0, 0, 0); __builtin_amdgcn_s_setprio(0); } while (0)
; #define PG8_WAIT_V(n) asm volatile("s_waitcnt vmcnt(" #n ")" ::: "memory")
; #define PG8_WAIT_L(n) asm volatile("s_waitcnt lgkmcnt(" #n ")" ::: "memory")
; #define PG8_BAR __builtin_amdgcn_s_barrier()
; #define PG8_SCHED __builtin_amdgcn_sched_barrier(0)
; template <class Epi, class Sched, bool ALIGN_EPI = false, bool SP2 = false>
; __device__ __forceinline__ void gemm_phase(PG8_LAS unsigned char* lds, const Gemm g, const Sched& S, const Epi& E, int wave_in) {
;     ...
;             PG8_WAIT_V(8); PG8_WAIT_L(0); PG8_BAR; PG8_MMA(1, 0, At, B0); PG8_MMA(1, 1, At, B1); PG8_BAR; PG8_SCHED;
;             PG8_LDB(B0, 1, 0); PG8_LDB(B1, 1, 1); PG8_SCHED; PG8_LDA(At, 1, 0); PG8_STAGE(PG8_SA(0, 1), a2 + hstepA, voffA);
;             PG8_WAIT_V(8); PG8_WAIT_L(0); PG8_BAR; PG8_MMA(0, 0, At, B0); PG8_MMA(0, 1, At, B1); PG8_BAR; PG8_SCHED;
	s_setprio 0
	s_waitcnt lgkmcnt(0)
	v_mfma_f32_16x16x32_bf16 v[94:97], v[106:109], v[182:185], v[94:97]
	v_mfma_f32_16x16x32_bf16 v[30:33], v[114:117], v[182:185], v[30:33]
	v_mfma_f32_16x16x32_bf16 v[86:89], v[106:109], v[190:193], v[86:89]
	v_mfma_f32_16x16x32_bf16 v[22:25], v[114:117], v[190:193], v[22:25]
	v_mfma_f32_16x16x32_bf16 v[78:81], v[106:109], v[222:225], v[78:81]
	v_mfma_f32_16x16x32_bf16 v[14:17], v[114:117], v[222:225], v[14:17]
	v_mfma_f32_16x16x32_bf16 v[70:73], v[106:109], v[230:233], v[70:73]
	v_mfma_f32_16x16x32_bf16 v[6:9], v[114:117], v[230:233], v[6:9]
	v_mfma_f32_16x16x32_bf16 v[94:97], v[110:113], v[186:189], v[94:97]
	v_mfma_f32_16x16x32_bf16 v[30:33], v[118:121], v[186:189], v[30:33]
	v_mfma_f32_16x16x32_bf16 v[86:89], v[110:113], v[218:221], v[86:89]
	v_mfma_f32_16x16x32_bf16 v[22:25], v[118:121], v[218:221], v[22:25]
	v_mfma_f32_16x16x32_bf16 v[78:81], v[110:113], v[226:229], v[78:81]
	v_mfma_f32_16x16x32_bf16 v[14:17], v[118:121], v[226:229], v[14:17]
	v_mfma_f32_16x16x32_bf16 v[70:73], v[110:113], v[234:237], v[70:73]
	v_mfma_f32_16x16x32_bf16 v[6:9], v[118:121], v[234:237], v[6:9]
	v_mfma_f32_16x16x32_bf16 v[90:93], v[122:125], v[182:185], v[90:93]
	v_mfma_f32_16x16x32_bf16 v[26:29], v[130:133], v[182:185], v[26:29]
	v_mfma_f32_16x16x32_bf16 v[82:85], v[122:125], v[190:193], v[82:85]
	v_mfma_f32_16x16x32_bf16 v[18:21], v[130:133], v[190:193], v[18:21]
	v_mfma_f32_16x16x32_bf16 v[74:77], v[122:125], v[222:225], v[74:77]
	v_mfma_f32_16x16x32_bf16 v[10:13], v[130:133], v[222:225], v[10:13]
	v_mfma_f32_16x16x32_bf16 v[66:69], v[122:125], v[230:233], v[66:69]
	v_mfma_f32_16x16x32_bf16 v[2:5], v[130:133], v[230:233], v[2:5]
	v_mfma_f32_16x16x32_bf16 v[90:93], v[126:129], v[186:189], v[90:93]
	v_mfma_f32_16x16x32_bf16 v[26:29], v[178:181], v[186:189], v[26:29]
	v_mfma_f32_16x16x32_bf16 v[82:85], v[126:129], v[218:221], v[82:85]
	v_mfma_f32_16x16x32_bf16 v[18:21], v[178:181], v[218:221], v[18:21]
	v_mfma_f32_16x16x32_bf16 v[74:77], v[126:129], v[226:229], v[74:77]
	v_mfma_f32_16x16x32_bf16 v[10:13], v[178:181], v[226:229], v[10:13]
	v_mfma_f32_16x16x32_bf16 v[66:69], v[126:129], v[234:237], v[66:69]
	v_mfma_f32_16x16x32_bf16 v[2:5], v[178:181], v[234:237], v[2:5]
	s_setprio 1
	s_barrier
	s_add_i32 s72, 0, 0x18000
	s_add_i32 s73, 0, 0x1c000
	v_add_u32_e32 v118, s72, v214
	v_add_u32_e32 v178, s73, v214
	ds_read_b128 v[106:109], v118
	ds_read_b128 v[110:113], v118 offset:1024
	ds_read_b128 v[114:117], v118 offset:2048
	ds_read_b128 v[118:121], v118 offset:3072
	ds_read_b128 v[122:125], v178
	ds_read_b128 v[126:129], v178 offset:1024
	ds_read_b128 v[130:133], v178 offset:2048
	ds_read_b128 v[178:181], v178 offset:3072
	s_add_u32 s52, s52, 0x80000
	s_addc_u32 s53, s53, 0
	s_mov_b32 m0, s60
	v_lshl_add_u64 v[246:247], s[52:53], 0, v[172:173]
	ds_read_b128 v[182:185], v217 offset:32768
	ds_read_b128 v[186:189], v217 offset:33792
	ds_read_b128 v[190:193], v217 offset:34816
	ds_read_b128 v[218:221], v217 offset:35840
	ds_read_b128 v[222:225], v217 offset:36864
	ds_read_b128 v[226:229], v217 offset:37888
	ds_read_b128 v[230:233], v217 offset:38912
	ds_read_b128 v[234:237], v217 offset:39936
	global_load_lds_dwordx4 v[246:247], off
	v_lshl_add_u64 v[246:247], s[52:53], 0, v[170:171]
	s_mov_b32 m0, s61
	s_nop 0
	global_load_lds_dwordx4 v[246:247], off
	s_waitcnt vmcnt(8)
	s_waitcnt lgkmcnt(0)
	s_barrier
	s_setprio 0
	s_waitcnt lgkmcnt(0)
	v_mfma_f32_16x16x32_bf16 v[154:157], v[106:109], v[182:185], v[154:157]
	v_mfma_f32_16x16x32_bf16 v[62:65], v[114:117], v[182:185], v[62:65]
	v_mfma_f32_16x16x32_bf16 v[150:153], v[106:109], v[190:193], v[150:153]
	v_mfma_f32_16x16x32_bf16 v[54:57], v[114:117], v[190:193], v[54:57]
	v_mfma_f32_16x16x32_bf16 v[142:145], v[106:109], v[222:225], v[142:145]
	v_mfma_f32_16x16x32_bf16 v[46:49], v[114:117], v[222:225], v[46:49]
	v_mfma_f32_16x16x32_bf16 v[102:105], v[106:109], v[230:233], v[102:105]
	v_mfma_f32_16x16x32_bf16 v[38:41], v[114:117], v[230:233], v[38:41]
	v_mfma_f32_16x16x32_bf16 v[154:157], v[110:113], v[186:189], v[154:157]
	v_mfma_f32_16x16x32_bf16 v[62:65], v[118:121], v[186:189], v[62:65]
	v_mfma_f32_16x16x32_bf16 v[150:153], v[110:113], v[218:221], v[150:153]
	v_mfma_f32_16x16x32_bf16 v[54:57], v[118:121], v[218:221], v[54:57]
	v_mfma_f32_16x16x32_bf16 v[142:145], v[110:113], v[226:229], v[142:145]
	v_mfma_f32_16x16x32_bf16 v[46:49], v[118:121], v[226:229], v[46:49]
	v_mfma_f32_16x16x32_bf16 v[102:105], v[110:113], v[234:237], v[102:105]
	v_mfma_f32_16x16x32_bf16 v[38:41], v[118:121], v[234:237], v[38:41]
	v_mfma_f32_16x16x32_bf16 v[134:137], v[122:125], v[182:185], v[134:137]
	v_mfma_f32_16x16x32_bf16 v[58:61], v[130:133], v[182:185], v[58:61]
	v_mfma_f32_16x16x32_bf16 v[146:149], v[122:125], v[190:193], v[146:149]
	v_mfma_f32_16x16x32_bf16 v[50:53], v[130:133], v[190:193], v[50:53]
	v_mfma_f32_16x16x32_bf16 v[138:141], v[122:125], v[222:225], v[138:141]
	v_mfma_f32_16x16x32_bf16 v[42:45], v[130:133], v[222:225], v[42:45]
	v_mfma_f32_16x16x32_bf16 v[98:101], v[122:125], v[230:233], v[98:101]
	v_mfma_f32_16x16x32_bf16 v[34:37], v[130:133], v[230:233], v[34:37]
	v_mfma_f32_16x16x32_bf16 v[134:137], v[126:129], v[186:189], v[134:137]
	v_mfma_f32_16x16x32_bf16 v[58:61], v[178:181], v[186:189], v[58:61]
	v_mfma_f32_16x16x32_bf16 v[146:149], v[126:129], v[218:221], v[146:149]
	v_mfma_f32_16x16x32_bf16 v[50:53], v[178:181], v[218:221], v[50:53]
	v_mfma_f32_16x16x32_bf16 v[138:141], v[126:129], v[226:229], v[138:141]
	v_mfma_f32_16x16x32_bf16 v[42:45], v[178:181], v[226:229], v[42:45]
	v_mfma_f32_16x16x32_bf16 v[98:101], v[126:129], v[234:237], v[98:101]
	v_mfma_f32_16x16x32_bf16 v[34:37], v[178:181], v[234:237], v[34:37]
	s_setprio 1
	s_barrier
; #define PG8_STAGE(bufoff, gbase, voff) do { _Pragma("unroll") for (int _i = 0; _i < 2; ++_i) \
;         __builtin_amdgcn_global_load_lds((const unsigned*)((const char*)(gbase) + (voff)[_i]), (PG8_LAS unsigned*)(lds + (bufoff) + ldsw + _i * 8192), 16, 0, 0); } while (0)
; #define PG8_LDA(dst, b, h) do { _Pragma("unroll") for (int m = 0; m < 4; ++m) _Pragma("unroll") for (int k = 0; k < 2; ++k) dst[m][k] = *(const PG8_LAS bf16x8*)(lds + PG8_SA(b, h) + aoff + m * 2048 + k * 1024); } while (0)
; #define PG8_MMA(ai, bj, At, Bt) do { __builtin_amdgcn_s_setprio(1); _Pragma("unroll") for (int m = 0; m < 4; ++m) _Pragma("unroll") for (int n = 0; n < 2; ++n) _Pragma("unroll") for (int k = 0; k < 2; ++k) \
;         acc[ai][bj][m][n] = __builtin_amdgcn_mfma_f32_16x16x32_bf16(Bt[n][k], At[m][k], acc[ai][bj][m][n], 0, 0, 0); __builtin_amdgcn_s_setprio(0); } while (0)
; #define PG8_WAIT_V(n) asm volatile("s_waitcnt vmcnt(" #n ")" ::: "memory")
; #define PG8_WAIT_L(n) asm volatile("s_waitcnt lgkmcnt(" #n ")" ::: "memory")
; #define PG8_BAR __builtin_amdgcn_s_barrier()
; #define PG8_SCHED __builtin_amdgcn_sched_barrier(0)
; template <class Epi, class Sched, bool ALIGN_EPI = false, bool SP2 = false>
; __device__ __forceinline__ void gemm_phase(PG8_LAS unsigned char* lds, const Gemm g, const Sched& S, const Epi& E, int wave_in) {
;     ...
;         for (int t = 0; t < nt; t += 2) {
;             const bool last = (t == nt - 2);
;             const char* a1 = cA + (size_t)(t + 1) * kstep;
;             const char* a2 = last ? nA : cA + (size_t)(t + 2) * kstep; const char* b2 = last ? nB : cB + (size_t)(t + 2) * kstep;
;     ...
;             PG8_LDA(At, 1, 1); PG8_STAGE(PG8_SB(1, 0), b3, voffB); PG8_STAGE(PG8_SB(1, 1), b3 + hstep, voffB); PG8_STAGE(PG8_SA(1, 0), a3, voffA);
;             PG8_WAIT_V(8); PG8_WAIT_L(0); PG8_BAR; PG8_MMA(1, 0, At, B0); PG8_MMA(1, 1, At, B1); PG8_BAR; PG8_SCHED;
	s_add_i32 s52, s72, s57
	v_lshl_add_u64 v[238:239], v[238:239], 0, s[84:85]
	s_mov_b32 m0, s52
	ds_read_b128 v[182:185], v217 offset:49152
	ds_read_b128 v[186:189], v217 offset:50176
	ds_read_b128 v[190:193], v217 offset:51200
	ds_read_b128 v[218:221], v217 offset:52224
	ds_read_b128 v[222:225], v217 offset:53248
	ds_read_b128 v[226:229], v217 offset:54272
	ds_read_b128 v[230:233], v217 offset:55296
	ds_read_b128 v[234:237], v217 offset:56320
	global_load_lds_dwordx4 v[238:239], off
	s_add_i32 m0, s52, 0x2000
	s_add_u32 s50, s50, 0x80080
	v_lshl_add_u64 v[238:239], v[240:241], 0, s[84:85]
	s_addc_u32 s51, s51, 0
	s_add_i32 s52, s73, s57
	global_load_lds_dwordx4 v[238:239], off
	v_lshl_add_u64 v[238:239], s[50:51], 0, v[0:1]
	s_mov_b32 m0, s52
	s_nop 0
	global_load_lds_dwordx4 v[238:239], off
	v_lshl_add_u64 v[238:239], s[50:51], 0, v[168:169]
	s_add_i32 m0, s52, 0x2000
	s_nop 0
	global_load_lds_dwordx4 v[238:239], off
	v_lshl_add_u64 v[238:239], v[242:243], 0, s[84:85]
	s_mov_b32 m0, s62
	s_nop 0
	global_load_lds_dwordx4 v[238:239], off
	v_lshl_add_u64 v[238:239], v[244:245], 0, s[84:85]
	s_mov_b32 m0, s63
	s_nop 0
	global_load_lds_dwordx4 v[238:239], off
	s_waitcnt vmcnt(8)
	s_waitcnt lgkmcnt(0)
	s_barrier
	s_setprio 0
	s_waitcnt lgkmcnt(0)
	v_mfma_f32_16x16x32_bf16 v[94:97], v[106:109], v[182:185], v[94:97]
	v_mfma_f32_16x16x32_bf16 v[30:33], v[114:117], v[182:185], v[30:33]
	v_mfma_f32_16x16x32_bf16 v[86:89], v[106:109], v[190:193], v[86:89]
	v_mfma_f32_16x16x32_bf16 v[22:25], v[114:117], v[190:193], v[22:25]
	v_mfma_f32_16x16x32_bf16 v[78:81], v[106:109], v[222:225], v[78:81]
	v_mfma_f32_16x16x32_bf16 v[14:17], v[114:117], v[222:225], v[14:17]
	v_mfma_f32_16x16x32_bf16 v[70:73], v[106:109], v[230:233], v[70:73]
	v_mfma_f32_16x16x32_bf16 v[6:9], v[114:117], v[230:233], v[6:9]
	v_mfma_f32_16x16x32_bf16 v[94:97], v[110:113], v[186:189], v[94:97]
	v_mfma_f32_16x16x32_bf16 v[30:33], v[118:121], v[186:189], v[30:33]
	v_mfma_f32_16x16x32_bf16 v[86:89], v[110:113], v[218:221], v[86:89]
	v_mfma_f32_16x16x32_bf16 v[22:25], v[118:121], v[218:221], v[22:25]
	v_mfma_f32_16x16x32_bf16 v[78:81], v[110:113], v[226:229], v[78:81]
	v_mfma_f32_16x16x32_bf16 v[14:17], v[118:121], v[226:229], v[14:17]
	v_mfma_f32_16x16x32_bf16 v[70:73], v[110:113], v[234:237], v[70:73]
	v_mfma_f32_16x16x32_bf16 v[6:9], v[118:121], v[234:237], v[6:9]
	v_mfma_f32_16x16x32_bf16 v[90:93], v[122:125], v[182:185], v[90:93]
	v_mfma_f32_16x16x32_bf16 v[26:29], v[130:133], v[182:185], v[26:29]
	v_mfma_f32_16x16x32_bf16 v[82:85], v[122:125], v[190:193], v[82:85]
	v_mfma_f32_16x16x32_bf16 v[18:21], v[130:133], v[190:193], v[18:21]
	v_mfma_f32_16x16x32_bf16 v[74:77], v[122:125], v[222:225], v[74:77]
	v_mfma_f32_16x16x32_bf16 v[10:13], v[130:133], v[222:225], v[10:13]
	v_mfma_f32_16x16x32_bf16 v[66:69], v[122:125], v[230:233], v[66:69]
	v_mfma_f32_16x16x32_bf16 v[2:5], v[130:133], v[230:233], v[2:5]
	v_mfma_f32_16x16x32_bf16 v[90:93], v[126:129], v[186:189], v[90:93]
	v_mfma_f32_16x16x32_bf16 v[26:29], v[178:181], v[186:189], v[26:29]
	v_mfma_f32_16x16x32_bf16 v[82:85], v[126:129], v[218:221], v[82:85]
	v_mfma_f32_16x16x32_bf16 v[18:21], v[178:181], v[218:221], v[18:21]
	v_mfma_f32_16x16x32_bf16 v[74:77], v[126:129], v[226:229], v[74:77]
	v_mfma_f32_16x16x32_bf16 v[10:13], v[178:181], v[226:229], v[10:13]
	v_mfma_f32_16x16x32_bf16 v[66:69], v[126:129], v[234:237], v[66:69]
	v_mfma_f32_16x16x32_bf16 v[2:5], v[178:181], v[234:237], v[2:5]
	s_setprio 1
	s_barrier
	s_add_i32 s71, s71, 2
	s_add_u32 s48, s48, 0x100
	s_addc_u32 s49, s49, 0
	s_add_u32 s69, s69, 0x100
	s_addc_u32 s70, s70, 0
	s_cmp_gt_u32 s71, 29
	s_cbranch_scc0 .LBB0_43
	s_and_b64 vcc, exec, s[24:25]
	s_cbranch_vccz .LBB0_46
	s_barrier

; #define PG8_STAGE(bufoff, gbase, voff) do { _Pragma("unroll") for (int _i = 0; _i < 2; ++_i) \
;         __builtin_amdgcn_global_load_lds((const unsigned*)((const char*)(gbase) + (voff)[_i]), (PG8_LAS unsigned*)(lds + (bufoff) + ldsw + _i * 8192), 16, 0, 0); } while (0)
; #define PG8_LDA(dst, b, h) do { _Pragma("unroll") for (int m = 0; m < 4; ++m) _Pragma("unroll") for (int k = 0; k < 2; ++k) dst[m][k] = *(const PG8_LAS bf16x8*)(lds + PG8_SA(b, h) + aoff + m * 2048 + k * 1024); } while (0)
; #define PG8_LDB(dst, b, h) do { _Pragma("unroll") for (int n = 0; n < 2; ++n) _Pragma("unroll") for (int k = 0; k < 2; ++k) dst[n][k] = *(const PG8_LAS bf16x8*)(lds + PG8_SB(b, h) + boff + n * 2048 + k * 1024); } while (0)
; #define PG8_WAIT_V(n) asm volatile("s_waitcnt vmcnt(" #n ")" ::: "memory")
; #define PG8_WAIT_L(n) asm volatile("s_waitcnt lgkmcnt(" #n ")" ::: "memory")
; #define PG8_BAR __builtin_amdgcn_s_barrier()
; #define PG8_SCHED __builtin_amdgcn_sched_barrier(0)
; template <class Epi, class Sched, bool ALIGN_EPI = false, bool SP2 = false>
; __device__ __forceinline__ void gemm_phase(PG8_LAS unsigned char* lds, const Gemm g, const Sched& S, const Epi& E, int wave_in) {
;     ...
;         const char* nA = has_next ? (const char*)g.A + (size_t)nxt.pm * tstepA : cA; const char* nB = has_next ? (const char*)g.Bt + (size_t)nxt.pn * tstep : cB;
;         for (int t = 0; t < nt; t += 2) {
;             const bool last = (t == nt - 2);
;             const char* a1 = cA + (size_t)(t + 1) * kstep;
;             const char* a2 = last ? nA : cA + (size_t)(t + 2) * kstep; const char* b2 = last ? nB : cB + (size_t)(t + 2) * kstep;
;             const char* a3 = a2 + kstep; const char* b3 = b2 + kstep;
;             if (last && has_next) S.a_ready(nxt);
;             if constexpr (SP2) {
;             PG8_LDB(B0, 0, 0); PG8_LDB(B1, 0, 1); PG8_SCHED; PG8_LDA(At, 0, 0); PG8_STAGE(PG8_SA(1, 1), a1 + hstepA, voffA);
;             PG8_WAIT_V(8); PG8_WAIT_L(0); PG8_BAR; PG8_MMA(0, 0, At, B0); PG8_MMA(0, 1, At, B1); PG8_BAR; PG8_SCHED;
;             PG8_LDA(At, 0, 1); PG8_STAGE(PG8_SB(0, 0), b2, voffB); PG8_STAGE(PG8_SB(0, 1), b2 + hstep, voffB); PG8_STAGE(PG8_SA(0, 0), a2, voffA);
;             PG8_WAIT_V(8); PG8_WAIT_L(0); PG8_BAR; PG8_MMA(1, 0, At, B0); PG8_MMA(1, 1, At, B1); PG8_BAR; PG8_SCHED;
.LBB0_84:
	s_add_u32 s24, s22, 0xfff80080
	s_addc_u32 s25, s23, -1
	s_add_i32 s47, 0, 0x10000
	s_cmp_eq_u32 s46, 12
	s_cselect_b32 s27, s17, s25
	s_cselect_b32 s26, s42, s24
	v_add_u32_e32 v144, s47, v147
	s_cselect_b32 s25, s11, s45
	s_cselect_b32 s24, s43, s44
	s_add_i32 s50, 0, 0x14000
	ds_read_b128 v[140:143], v144
	ds_read_b128 v[150:153], v144 offset:1024
	ds_read_b128 v[154:157], v144 offset:2048
	ds_read_b128 v[168:171], v144 offset:3072
	v_add_u32_e32 v144, s50, v147
	ds_read_b128 v[172:175], v144
	ds_read_b128 v[176:179], v144 offset:1024
	ds_read_b128 v[180:183], v144 offset:2048
	ds_read_b128 v[184:187], v144 offset:3072
	v_lshl_add_u64 v[144:145], s[22:23], 0, v[136:137]
	s_add_i32 m0, s31, 0xc000
	ds_read_b128 v[188:191], v149
	ds_read_b128 v[212:215], v149 offset:1024
	ds_read_b128 v[216:219], v149 offset:2048
	ds_read_b128 v[220:223], v149 offset:3072
	ds_read_b128 v[224:227], v149 offset:4096
	ds_read_b128 v[228:231], v149 offset:5120
	ds_read_b128 v[232:235], v149 offset:6144
	ds_read_b128 v[236:239], v149 offset:7168
	global_load_lds_dwordx4 v[144:145], off
	v_lshl_add_u64 v[144:145], s[22:23], 0, v[138:139]
	s_add_i32 m0, s31, 0xe000
	s_nop 0
	global_load_lds_dwordx4 v[144:145], off
	s_waitcnt vmcnt(8)
	s_waitcnt lgkmcnt(0)
	s_barrier
	s_setprio 0
	s_waitcnt lgkmcnt(0)
	v_mfma_f32_16x16x32_bf16 v[126:129], v[140:143], v[188:191], v[126:129]
	v_mfma_f32_16x16x32_bf16 v[122:125], v[154:157], v[188:191], v[122:125]
	v_mfma_f32_16x16x32_bf16 v[118:121], v[140:143], v[216:219], v[118:121]
	v_mfma_f32_16x16x32_bf16 v[106:109], v[154:157], v[216:219], v[106:109]
	v_mfma_f32_16x16x32_bf16 v[102:105], v[140:143], v[224:227], v[102:105]
	v_mfma_f32_16x16x32_bf16 v[90:93], v[154:157], v[224:227], v[90:93]
	v_mfma_f32_16x16x32_bf16 v[86:89], v[140:143], v[232:235], v[86:89]
	v_mfma_f32_16x16x32_bf16 v[74:77], v[154:157], v[232:235], v[74:77]
	v_mfma_f32_16x16x32_bf16 v[126:129], v[150:153], v[212:215], v[126:129]
	v_mfma_f32_16x16x32_bf16 v[122:125], v[168:171], v[212:215], v[122:125]
	v_mfma_f32_16x16x32_bf16 v[118:121], v[150:153], v[220:223], v[118:121]
	v_mfma_f32_16x16x32_bf16 v[106:109], v[168:171], v[220:223], v[106:109]
	v_mfma_f32_16x16x32_bf16 v[102:105], v[150:153], v[228:231], v[102:105]
	v_mfma_f32_16x16x32_bf16 v[90:93], v[168:171], v[228:231], v[90:93]
	v_mfma_f32_16x16x32_bf16 v[86:89], v[150:153], v[236:239], v[86:89]
	v_mfma_f32_16x16x32_bf16 v[74:77], v[168:171], v[236:239], v[74:77]
	v_mfma_f32_16x16x32_bf16 v[114:117], v[172:175], v[188:191], v[114:117]
	v_mfma_f32_16x16x32_bf16 v[110:113], v[180:183], v[188:191], v[110:113]
	v_mfma_f32_16x16x32_bf16 v[98:101], v[172:175], v[216:219], v[98:101]
	v_mfma_f32_16x16x32_bf16 v[94:97], v[180:183], v[216:219], v[94:97]
	v_mfma_f32_16x16x32_bf16 v[82:85], v[172:175], v[224:227], v[82:85]
	v_mfma_f32_16x16x32_bf16 v[78:81], v[180:183], v[224:227], v[78:81]
	v_mfma_f32_16x16x32_bf16 v[70:73], v[172:175], v[232:235], v[70:73]
	v_mfma_f32_16x16x32_bf16 v[66:69], v[180:183], v[232:235], v[66:69]
	v_mfma_f32_16x16x32_bf16 v[114:117], v[176:179], v[212:215], v[114:117]
	v_mfma_f32_16x16x32_bf16 v[110:113], v[184:187], v[212:215], v[110:113]
	v_mfma_f32_16x16x32_bf16 v[98:101], v[176:179], v[220:223], v[98:101]
	v_mfma_f32_16x16x32_bf16 v[94:97], v[184:187], v[220:223], v[94:97]
	v_mfma_f32_16x16x32_bf16 v[82:85], v[176:179], v[228:231], v[82:85]
	v_mfma_f32_16x16x32_bf16 v[78:81], v[184:187], v[228:231], v[78:81]
	v_mfma_f32_16x16x32_bf16 v[70:73], v[176:179], v[236:239], v[70:73]
	v_mfma_f32_16x16x32_bf16 v[66:69], v[184:187], v[236:239], v[66:69]
	s_setprio 1
	s_barrier
	s_add_i32 s47, s47, s30
	v_lshl_add_u64 v[144:145], s[24:25], 0, v[0:1]
	s_mov_b32 m0, s47
	ds_read_b128 v[188:191], v149 offset:16384
	ds_read_b128 v[212:215], v149 offset:17408
	ds_read_b128 v[216:219], v149 offset:18432
	ds_read_b128 v[220:223], v149 offset:19456
	ds_read_b128 v[224:227], v149 offset:20480
	ds_read_b128 v[228:231], v149 offset:21504
	ds_read_b128 v[232:235], v149 offset:22528
	ds_read_b128 v[236:239], v149 offset:23552
	global_load_lds_dwordx4 v[144:145], off
	s_add_i32 m0, s47, 0x2000
	s_add_u32 s48, s24, 0x40000
	v_lshl_add_u64 v[192:193], s[24:25], 0, v[130:131]
	s_addc_u32 s49, s25, 0
	s_add_i32 s47, s50, s30
	global_load_lds_dwordx4 v[192:193], off
	v_lshl_add_u64 v[240:241], s[48:49], 0, v[0:1]
	s_mov_b32 m0, s47
	v_lshl_add_u64 v[242:243], s[26:27], 0, v[132:133]
	global_load_lds_dwordx4 v[240:241], off
	v_lshl_add_u64 v[240:241], s[48:49], 0, v[130:131]
	s_add_i32 m0, s47, 0x2000
	s_nop 0
	global_load_lds_dwordx4 v[240:241], off
	v_lshl_add_u64 v[240:241], s[26:27], 0, v[134:135]
	s_mov_b32 m0, s31
	s_nop 0
	global_load_lds_dwordx4 v[240:241], off
	s_mov_b32 m0, s34
	s_nop 0
	global_load_lds_dwordx4 v[242:243], off
	s_waitcnt vmcnt(8)
	s_waitcnt lgkmcnt(0)
	s_barrier
; #define PG8_STAGE(bufoff, gbase, voff) do { _Pragma("unroll") for (int _i = 0; _i < 2; ++_i) \
;         __builtin_amdgcn_global_load_lds((const unsigned*)((const char*)(gbase) + (voff)[_i]), (PG8_LAS unsigned*)(lds + (bufoff) + ldsw + _i * 8192), 16, 0, 0); } while (0)
; #define PG8_LDA(dst, b, h) do { _Pragma("unroll") for (int m = 0; m < 4; ++m) _Pragma("unroll") for (int k = 0; k < 2; ++k) dst[m][k] = *(const PG8_LAS bf16x8*)(lds + PG8_SA(b, h) + aoff + m * 2048 + k * 1024); } while (0)
; #define PG8_LDB(dst, b, h) do { _Pragma("unroll") for (int n = 0; n < 2; ++n) _Pragma("unroll") for (int k = 0; k < 2; ++k) dst[n][k] = *(const PG8_LAS bf16x8*)(lds + PG8_SB(b, h) + boff + n * 2048 + k * 1024); } while (0)
; #define PG8_MMA(ai, bj, At, Bt) do { __builtin_amdgcn_s_setprio(1); _Pragma("unroll") for (int m = 0; m < 4; ++m) _Pragma("unroll") for (int n = 0; n < 2; ++n) _Pragma("unroll") for (int k = 0; k < 2; ++k) \
;         acc[ai][bj][m][n] = __builtin_amdgcn_mfma_f32_16x16x32_bf16(Bt[n][k], At[m][k], acc[ai][bj][m][n], 0, 0, 0); __builtin_amdgcn_s_setprio(0); } while (0)
; #define PG8_WAIT_V(n) asm volatile("s_waitcnt vmcnt(" #n ")" ::: "memory")
; #define PG8_WAIT_L(n) asm volatile("s_waitcnt lgkmcnt(" #n ")" ::: "memory")
; #define PG8_BAR __builtin_amdgcn_s_barrier()
; #define PG8_SCHED __builtin_amdgcn_sched_barrier(0)
; template <class Epi, class Sched, bool ALIGN_EPI = false, bool SP2 = false>
; __device__ __forceinline__ void gemm_phase(PG8_LAS unsigned char* lds, const Gemm g, const Sched& S, const Epi& E, int wave_in) {
;     ...
;             PG8_WAIT_V(8); PG8_WAIT_L(0); PG8_BAR; PG8_MMA(1, 0, At, B0); PG8_MMA(1, 1, At, B1); PG8_BAR; PG8_SCHED;
;             PG8_LDB(B0, 1, 0); PG8_LDB(B1, 1, 1); PG8_SCHED; PG8_LDA(At, 1, 0); PG8_STAGE(PG8_SA(0, 1), a2 + hstepA, voffA);
;             PG8_WAIT_V(8); PG8_WAIT_L(0); PG8_BAR; PG8_MMA(0, 0, At, B0); PG8_MMA(0, 1, At, B1); PG8_BAR; PG8_SCHED;
	s_setprio 0
	s_waitcnt lgkmcnt(0)
	v_mfma_f32_16x16x32_bf16 v[62:65], v[140:143], v[188:191], v[62:65]
	v_mfma_f32_16x16x32_bf16 v[58:61], v[154:157], v[188:191], v[58:61]
	v_mfma_f32_16x16x32_bf16 v[54:57], v[140:143], v[216:219], v[54:57]
	v_mfma_f32_16x16x32_bf16 v[42:45], v[154:157], v[216:219], v[42:45]
	v_mfma_f32_16x16x32_bf16 v[38:41], v[140:143], v[224:227], v[38:41]
	v_mfma_f32_16x16x32_bf16 v[26:29], v[154:157], v[224:227], v[26:29]
	v_mfma_f32_16x16x32_bf16 v[22:25], v[140:143], v[232:235], v[22:25]
	v_mfma_f32_16x16x32_bf16 v[10:13], v[154:157], v[232:235], v[10:13]
	v_mfma_f32_16x16x32_bf16 v[62:65], v[150:153], v[212:215], v[62:65]
	v_mfma_f32_16x16x32_bf16 v[58:61], v[168:171], v[212:215], v[58:61]
	v_mfma_f32_16x16x32_bf16 v[54:57], v[150:153], v[220:223], v[54:57]
	v_mfma_f32_16x16x32_bf16 v[42:45], v[168:171], v[220:223], v[42:45]
	v_mfma_f32_16x16x32_bf16 v[38:41], v[150:153], v[228:231], v[38:41]
	v_mfma_f32_16x16x32_bf16 v[26:29], v[168:171], v[228:231], v[26:29]
	v_mfma_f32_16x16x32_bf16 v[22:25], v[150:153], v[236:239], v[22:25]
	v_mfma_f32_16x16x32_bf16 v[10:13], v[168:171], v[236:239], v[10:13]
	v_mfma_f32_16x16x32_bf16 v[50:53], v[172:175], v[188:191], v[50:53]
	v_mfma_f32_16x16x32_bf16 v[46:49], v[180:183], v[188:191], v[46:49]
	v_mfma_f32_16x16x32_bf16 v[34:37], v[172:175], v[216:219], v[34:37]
	v_mfma_f32_16x16x32_bf16 v[30:33], v[180:183], v[216:219], v[30:33]
	v_mfma_f32_16x16x32_bf16 v[18:21], v[172:175], v[224:227], v[18:21]
	v_mfma_f32_16x16x32_bf16 v[14:17], v[180:183], v[224:227], v[14:17]
	v_mfma_f32_16x16x32_bf16 v[6:9], v[172:175], v[232:235], v[6:9]
	v_mfma_f32_16x16x32_bf16 v[2:5], v[180:183], v[232:235], v[2:5]
	v_mfma_f32_16x16x32_bf16 v[50:53], v[176:179], v[212:215], v[50:53]
	v_mfma_f32_16x16x32_bf16 v[46:49], v[184:187], v[212:215], v[46:49]
	v_mfma_f32_16x16x32_bf16 v[34:37], v[176:179], v[220:223], v[34:37]
	v_mfma_f32_16x16x32_bf16 v[30:33], v[184:187], v[220:223], v[30:33]
	v_mfma_f32_16x16x32_bf16 v[18:21], v[176:179], v[228:231], v[18:21]
	v_mfma_f32_16x16x32_bf16 v[14:17], v[184:187], v[228:231], v[14:17]
	v_mfma_f32_16x16x32_bf16 v[6:9], v[176:179], v[236:239], v[6:9]
	v_mfma_f32_16x16x32_bf16 v[2:5], v[184:187], v[236:239], v[2:5]
	s_setprio 1
	s_barrier
	s_add_i32 s47, 0, 0x18000
	s_add_i32 s48, 0, 0x1c000
	v_add_u32_e32 v168, s47, v147
	v_add_u32_e32 v184, s48, v147
	ds_read_b128 v[140:143], v168
	ds_read_b128 v[150:153], v168 offset:1024
	ds_read_b128 v[154:157], v168 offset:2048
	ds_read_b128 v[168:171], v168 offset:3072
	ds_read_b128 v[172:175], v184
	ds_read_b128 v[176:179], v184 offset:1024
	ds_read_b128 v[180:183], v184 offset:2048
	ds_read_b128 v[184:187], v184 offset:3072
	s_add_u32 s26, s26, 0x80000
	s_addc_u32 s27, s27, 0
	s_mov_b32 m0, s35
	v_lshl_add_u64 v[244:245], s[26:27], 0, v[134:135]
	ds_read_b128 v[188:191], v149 offset:32768
	ds_read_b128 v[212:215], v149 offset:33792
	ds_read_b128 v[216:219], v149 offset:34816
	ds_read_b128 v[220:223], v149 offset:35840
	ds_read_b128 v[224:227], v149 offset:36864
	ds_read_b128 v[228:231], v149 offset:37888
	ds_read_b128 v[232:235], v149 offset:38912
	ds_read_b128 v[236:239], v149 offset:39936
	global_load_lds_dwordx4 v[244:245], off
	v_lshl_add_u64 v[244:245], s[26:27], 0, v[132:133]
	s_mov_b32 m0, s36
	s_nop 0
	global_load_lds_dwordx4 v[244:245], off
	s_waitcnt vmcnt(8)
	s_waitcnt lgkmcnt(0)
	s_barrier
	s_setprio 0
	s_waitcnt lgkmcnt(0)
	v_mfma_f32_16x16x32_bf16 v[126:129], v[140:143], v[188:191], v[126:129]
	v_mfma_f32_16x16x32_bf16 v[122:125], v[154:157], v[188:191], v[122:125]
	v_mfma_f32_16x16x32_bf16 v[118:121], v[140:143], v[216:219], v[118:121]
	v_mfma_f32_16x16x32_bf16 v[106:109], v[154:157], v[216:219], v[106:109]
	v_mfma_f32_16x16x32_bf16 v[102:105], v[140:143], v[224:227], v[102:105]
	v_mfma_f32_16x16x32_bf16 v[90:93], v[154:157], v[224:227], v[90:93]
	v_mfma_f32_16x16x32_bf16 v[86:89], v[140:143], v[232:235], v[86:89]
	v_mfma_f32_16x16x32_bf16 v[74:77], v[154:157], v[232:235], v[74:77]
	v_mfma_f32_16x16x32_bf16 v[126:129], v[150:153], v[212:215], v[126:129]
	v_mfma_f32_16x16x32_bf16 v[122:125], v[168:171], v[212:215], v[122:125]
	v_mfma_f32_16x16x32_bf16 v[118:121], v[150:153], v[220:223], v[118:121]
	v_mfma_f32_16x16x32_bf16 v[106:109], v[168:171], v[220:223], v[106:109]
	v_mfma_f32_16x16x32_bf16 v[102:105], v[150:153], v[228:231], v[102:105]
	v_mfma_f32_16x16x32_bf16 v[90:93], v[168:171], v[228:231], v[90:93]
	v_mfma_f32_16x16x32_bf16 v[86:89], v[150:153], v[236:239], v[86:89]
	v_mfma_f32_16x16x32_bf16 v[74:77], v[168:171], v[236:239], v[74:77]
	v_mfma_f32_16x16x32_bf16 v[114:117], v[172:175], v[188:191], v[114:117]
	v_mfma_f32_16x16x32_bf16 v[110:113], v[180:183], v[188:191], v[110:113]
	v_mfma_f32_16x16x32_bf16 v[98:101], v[172:175], v[216:219], v[98:101]
	v_mfma_f32_16x16x32_bf16 v[94:97], v[180:183], v[216:219], v[94:97]
	v_mfma_f32_16x16x32_bf16 v[82:85], v[172:175], v[224:227], v[82:85]
	v_mfma_f32_16x16x32_bf16 v[78:81], v[180:183], v[224:227], v[78:81]
	v_mfma_f32_16x16x32_bf16 v[70:73], v[172:175], v[232:235], v[70:73]
	v_mfma_f32_16x16x32_bf16 v[66:69], v[180:183], v[232:235], v[66:69]
	v_mfma_f32_16x16x32_bf16 v[114:117], v[176:179], v[212:215], v[114:117]
	v_mfma_f32_16x16x32_bf16 v[110:113], v[184:187], v[212:215], v[110:113]
	v_mfma_f32_16x16x32_bf16 v[98:101], v[176:179], v[220:223], v[98:101]
	v_mfma_f32_16x16x32_bf16 v[94:97], v[184:187], v[220:223], v[94:97]
	v_mfma_f32_16x16x32_bf16 v[82:85], v[176:179], v[228:231], v[82:85]
	v_mfma_f32_16x16x32_bf16 v[78:81], v[184:187], v[228:231], v[78:81]
	v_mfma_f32_16x16x32_bf16 v[70:73], v[176:179], v[236:239], v[70:73]
	v_mfma_f32_16x16x32_bf16 v[66:69], v[184:187], v[236:239], v[66:69]
	s_setprio 1
	s_barrier
; #define PG8_STAGE(bufoff, gbase, voff) do { _Pragma("unroll") for (int _i = 0; _i < 2; ++_i) \
;         __builtin_amdgcn_global_load_lds((const unsigned*)((const char*)(gbase) + (voff)[_i]), (PG8_LAS unsigned*)(lds + (bufoff) + ldsw + _i * 8192), 16, 0, 0); } while (0)
; #define PG8_LDA(dst, b, h) do { _Pragma("unroll") for (int m = 0; m < 4; ++m) _Pragma("unroll") for (int k = 0; k < 2; ++k) dst[m][k] = *(const PG8_LAS bf16x8*)(lds + PG8_SA(b, h) + aoff + m * 2048 + k * 1024); } while (0)
; #define PG8_MMA(ai, bj, At, Bt) do { __builtin_amdgcn_s_setprio(1); _Pragma("unroll") for (int m = 0; m < 4; ++m) _Pragma("unroll") for (int n = 0; n < 2; ++n) _Pragma("unroll") for (int k = 0; k < 2; ++k) \
;         acc[ai][bj][m][n] = __builtin_amdgcn_mfma_f32_16x16x32_bf16(Bt[n][k], At[m][k], acc[ai][bj][m][n], 0, 0, 0); __builtin_amdgcn_s_setprio(0); } while (0)
; #define PG8_WAIT_V(n) asm volatile("s_waitcnt vmcnt(" #n ")" ::: "memory")
; #define PG8_WAIT_L(n) asm volatile("s_waitcnt lgkmcnt(" #n ")" ::: "memory")
; #define PG8_BAR __builtin_amdgcn_s_barrier()
; #define PG8_SCHED __builtin_amdgcn_sched_barrier(0)
; template <class Epi, class Sched, bool ALIGN_EPI = false, bool SP2 = false>
; __device__ __forceinline__ void gemm_phase(PG8_LAS unsigned char* lds, const Gemm g, const Sched& S, const Epi& E, int wave_in) {
;     ...
;         for (int t = 0; t < nt; t += 2) {
;             const bool last = (t == nt - 2);
;             const char* a1 = cA + (size_t)(t + 1) * kstep;
;             const char* a2 = last ? nA : cA + (size_t)(t + 2) * kstep; const char* b2 = last ? nB : cB + (size_t)(t + 2) * kstep;
;     ...
;             PG8_LDA(At, 1, 1); PG8_STAGE(PG8_SB(1, 0), b3, voffB); PG8_STAGE(PG8_SB(1, 1), b3 + hstep, voffB); PG8_STAGE(PG8_SA(1, 0), a3, voffA);
;             PG8_WAIT_V(8); PG8_WAIT_L(0); PG8_BAR; PG8_MMA(1, 0, At, B0); PG8_MMA(1, 1, At, B1); PG8_BAR; PG8_SCHED;
	s_add_i32 s26, s47, s30
	v_lshl_add_u64 v[144:145], v[144:145], 0, s[84:85]
	s_mov_b32 m0, s26
	ds_read_b128 v[188:191], v149 offset:49152
	ds_read_b128 v[212:215], v149 offset:50176
	ds_read_b128 v[216:219], v149 offset:51200
	ds_read_b128 v[220:223], v149 offset:52224
	ds_read_b128 v[224:227], v149 offset:53248
	ds_read_b128 v[228:231], v149 offset:54272
	ds_read_b128 v[232:235], v149 offset:55296
	ds_read_b128 v[236:239], v149 offset:56320
	global_load_lds_dwordx4 v[144:145], off
	s_add_i32 m0, s26, 0x2000
	s_add_u32 s24, s24, 0x40080
	v_lshl_add_u64 v[144:145], v[192:193], 0, s[84:85]
	s_addc_u32 s25, s25, 0
	s_add_i32 s26, s48, s30
	global_load_lds_dwordx4 v[144:145], off
	v_lshl_add_u64 v[144:145], s[24:25], 0, v[0:1]
	s_mov_b32 m0, s26
	s_nop 0
	global_load_lds_dwordx4 v[144:145], off
	v_lshl_add_u64 v[144:145], s[24:25], 0, v[130:131]
	s_add_i32 m0, s26, 0x2000
	s_nop 0
	global_load_lds_dwordx4 v[144:145], off
	v_lshl_add_u64 v[144:145], v[240:241], 0, s[84:85]
	s_mov_b32 m0, s37
	s_nop 0
	global_load_lds_dwordx4 v[144:145], off
	v_lshl_add_u64 v[144:145], v[242:243], 0, s[84:85]
	s_mov_b32 m0, s38
	s_nop 0
	global_load_lds_dwordx4 v[144:145], off
	s_waitcnt vmcnt(8)
	s_waitcnt lgkmcnt(0)
	s_barrier
	s_setprio 0
	s_waitcnt lgkmcnt(0)
	v_mfma_f32_16x16x32_bf16 v[62:65], v[140:143], v[188:191], v[62:65]
	v_mfma_f32_16x16x32_bf16 v[58:61], v[154:157], v[188:191], v[58:61]
	v_mfma_f32_16x16x32_bf16 v[54:57], v[140:143], v[216:219], v[54:57]
	v_mfma_f32_16x16x32_bf16 v[42:45], v[154:157], v[216:219], v[42:45]
	v_mfma_f32_16x16x32_bf16 v[38:41], v[140:143], v[224:227], v[38:41]
	v_mfma_f32_16x16x32_bf16 v[26:29], v[154:157], v[224:227], v[26:29]
	v_mfma_f32_16x16x32_bf16 v[22:25], v[140:143], v[232:235], v[22:25]
	v_mfma_f32_16x16x32_bf16 v[10:13], v[154:157], v[232:235], v[10:13]
	v_mfma_f32_16x16x32_bf16 v[62:65], v[150:153], v[212:215], v[62:65]
	v_mfma_f32_16x16x32_bf16 v[58:61], v[168:171], v[212:215], v[58:61]
	v_mfma_f32_16x16x32_bf16 v[54:57], v[150:153], v[220:223], v[54:57]
	v_mfma_f32_16x16x32_bf16 v[42:45], v[168:171], v[220:223], v[42:45]
	v_mfma_f32_16x16x32_bf16 v[38:41], v[150:153], v[228:231], v[38:41]
	v_mfma_f32_16x16x32_bf16 v[26:29], v[168:171], v[228:231], v[26:29]
	v_mfma_f32_16x16x32_bf16 v[22:25], v[150:153], v[236:239], v[22:25]
	v_mfma_f32_16x16x32_bf16 v[10:13], v[168:171], v[236:239], v[10:13]
	v_mfma_f32_16x16x32_bf16 v[50:53], v[172:175], v[188:191], v[50:53]
	v_mfma_f32_16x16x32_bf16 v[46:49], v[180:183], v[188:191], v[46:49]
	v_mfma_f32_16x16x32_bf16 v[34:37], v[172:175], v[216:219], v[34:37]
	v_mfma_f32_16x16x32_bf16 v[30:33], v[180:183], v[216:219], v[30:33]
	v_mfma_f32_16x16x32_bf16 v[18:21], v[172:175], v[224:227], v[18:21]
	v_mfma_f32_16x16x32_bf16 v[14:17], v[180:183], v[224:227], v[14:17]
	v_mfma_f32_16x16x32_bf16 v[6:9], v[172:175], v[232:235], v[6:9]
	v_mfma_f32_16x16x32_bf16 v[2:5], v[180:183], v[232:235], v[2:5]
	v_mfma_f32_16x16x32_bf16 v[50:53], v[176:179], v[212:215], v[50:53]
	v_mfma_f32_16x16x32_bf16 v[46:49], v[184:187], v[212:215], v[46:49]
	v_mfma_f32_16x16x32_bf16 v[34:37], v[176:179], v[220:223], v[34:37]
	v_mfma_f32_16x16x32_bf16 v[30:33], v[184:187], v[220:223], v[30:33]
	v_mfma_f32_16x16x32_bf16 v[18:21], v[176:179], v[228:231], v[18:21]
	v_mfma_f32_16x16x32_bf16 v[14:17], v[184:187], v[228:231], v[14:17]
	v_mfma_f32_16x16x32_bf16 v[6:9], v[176:179], v[236:239], v[6:9]
	v_mfma_f32_16x16x32_bf16 v[2:5], v[184:187], v[236:239], v[2:5]
	s_setprio 1
	s_barrier
	s_add_i32 s46, s46, 2
	s_add_u32 s22, s22, 0x100
	s_addc_u32 s23, s23, 0
	s_add_u32 s44, s44, 0x100
	s_addc_u32 s45, s45, 0
	s_cmp_gt_u32 s46, 13
	s_cbranch_scc0 .LBB0_84
	s_and_b64 vcc, exec, s[8:9]
	v_readlane_b32 s26, v254, 6
	v_readlane_b32 s27, v254, 7
	s_cbranch_vccz .LBB0_87
	s_barrier

; #define PG8_STAGE(bufoff, gbase, voff) do { _Pragma("unroll") for (int _i = 0; _i < 2; ++_i) \
;         __builtin_amdgcn_global_load_lds((const unsigned*)((const char*)(gbase) + (voff)[_i]), (PG8_LAS unsigned*)(lds + (bufoff) + ldsw + _i * 8192), 16, 0, 0); } while (0)
; #define PG8_LDA(dst, b, h) do { _Pragma("unroll") for (int m = 0; m < 4; ++m) _Pragma("unroll") for (int k = 0; k < 2; ++k) dst[m][k] = *(const PG8_LAS bf16x8*)(lds + PG8_SA(b, h) + aoff + m * 2048 + k * 1024); } while (0)
; #define PG8_LDB(dst, b, h) do { _Pragma("unroll") for (int n = 0; n < 2; ++n) _Pragma("unroll") for (int k = 0; k < 2; ++k) dst[n][k] = *(const PG8_LAS bf16x8*)(lds + PG8_SB(b, h) + boff + n * 2048 + k * 1024); } while (0)
; #define PG8_WAIT_V(n) asm volatile("s_waitcnt vmcnt(" #n ")" ::: "memory")
; #define PG8_WAIT_L(n) asm volatile("s_waitcnt lgkmcnt(" #n ")" ::: "memory")
; #define PG8_BAR __builtin_amdgcn_s_barrier()
; #define PG8_SCHED __builtin_amdgcn_sched_barrier(0)
; template <class Epi, class Sched, bool ALIGN_EPI = false, bool SP2 = false>
; __device__ __forceinline__ void gemm_phase(PG8_LAS unsigned char* lds, const Gemm g, const Sched& S, const Epi& E, int wave_in) {
;     ...
;         const char* nA = has_next ? (const char*)g.A + (size_t)nxt.pm * tstepA : cA; const char* nB = has_next ? (const char*)g.Bt + (size_t)nxt.pn * tstep : cB;
;         for (int t = 0; t < nt; t += 2) {
;             const bool last = (t == nt - 2);
;             const char* a1 = cA + (size_t)(t + 1) * kstep;
;             const char* a2 = last ? nA : cA + (size_t)(t + 2) * kstep; const char* b2 = last ? nB : cB + (size_t)(t + 2) * kstep;
;             const char* a3 = a2 + kstep; const char* b3 = b2 + kstep;
;             if (last && has_next) S.a_ready(nxt);
;             if constexpr (SP2) {
;             PG8_LDB(B0, 0, 0); PG8_LDB(B1, 0, 1); PG8_SCHED; PG8_LDA(At, 0, 0); PG8_STAGE(PG8_SA(1, 1), a1 + hstepA, voffA);
;             PG8_WAIT_V(8); PG8_WAIT_L(0); PG8_BAR; PG8_MMA(0, 0, At, B0); PG8_MMA(0, 1, At, B1); PG8_BAR; PG8_SCHED;
;             PG8_LDA(At, 0, 1); PG8_STAGE(PG8_SB(0, 0), b2, voffB); PG8_STAGE(PG8_SB(0, 1), b2 + hstep, voffB); PG8_STAGE(PG8_SA(0, 0), a2, voffA);
;             PG8_WAIT_V(8); PG8_WAIT_L(0); PG8_BAR; PG8_MMA(1, 0, At, B0); PG8_MMA(1, 1, At, B1); PG8_BAR; PG8_SCHED;
.LBB0_107:
	s_add_u32 s28, s26, 0xfff80080
	s_addc_u32 s29, s27, -1
	s_add_i32 s55, 0, 0x10000
	s_cmp_eq_u32 s54, 4
	s_cselect_b32 s31, s21, s29
	s_cselect_b32 s30, s50, s28
	v_add_u32_e32 v144, s55, v147
	s_cselect_b32 s29, s19, s53
	s_cselect_b32 s28, s51, s52
	s_add_i32 s58, 0, 0x14000
	ds_read_b128 v[140:143], v144
	ds_read_b128 v[150:153], v144 offset:1024
	ds_read_b128 v[154:157], v144 offset:2048
	ds_read_b128 v[168:171], v144 offset:3072
	v_add_u32_e32 v144, s58, v147
	ds_read_b128 v[172:175], v144
	ds_read_b128 v[176:179], v144 offset:1024
	ds_read_b128 v[180:183], v144 offset:2048
	ds_read_b128 v[184:187], v144 offset:3072
	v_lshl_add_u64 v[144:145], s[26:27], 0, v[136:137]
	s_add_i32 m0, s41, 0xc000
	ds_read_b128 v[188:191], v149
	ds_read_b128 v[212:215], v149 offset:1024
	ds_read_b128 v[216:219], v149 offset:2048
	ds_read_b128 v[220:223], v149 offset:3072
	ds_read_b128 v[224:227], v149 offset:4096
	ds_read_b128 v[228:231], v149 offset:5120
	ds_read_b128 v[232:235], v149 offset:6144
	ds_read_b128 v[236:239], v149 offset:7168
	global_load_lds_dwordx4 v[144:145], off
	v_lshl_add_u64 v[144:145], s[26:27], 0, v[138:139]
	s_add_i32 m0, s41, 0xe000
	s_nop 0
	global_load_lds_dwordx4 v[144:145], off
	s_waitcnt vmcnt(8)
	s_waitcnt lgkmcnt(0)
	s_barrier
	s_setprio 0
	s_waitcnt lgkmcnt(0)
	v_mfma_f32_16x16x32_bf16 v[126:129], v[140:143], v[188:191], v[126:129]
	v_mfma_f32_16x16x32_bf16 v[122:125], v[154:157], v[188:191], v[122:125]
	v_mfma_f32_16x16x32_bf16 v[110:113], v[140:143], v[216:219], v[110:113]
	v_mfma_f32_16x16x32_bf16 v[106:109], v[154:157], v[216:219], v[106:109]
	v_mfma_f32_16x16x32_bf16 v[94:97], v[140:143], v[224:227], v[94:97]
	v_mfma_f32_16x16x32_bf16 v[90:93], v[154:157], v[224:227], v[90:93]
	v_mfma_f32_16x16x32_bf16 v[78:81], v[140:143], v[232:235], v[78:81]
	v_mfma_f32_16x16x32_bf16 v[74:77], v[154:157], v[232:235], v[74:77]
	v_mfma_f32_16x16x32_bf16 v[126:129], v[150:153], v[212:215], v[126:129]
	v_mfma_f32_16x16x32_bf16 v[122:125], v[168:171], v[212:215], v[122:125]
	v_mfma_f32_16x16x32_bf16 v[110:113], v[150:153], v[220:223], v[110:113]
	v_mfma_f32_16x16x32_bf16 v[106:109], v[168:171], v[220:223], v[106:109]
	v_mfma_f32_16x16x32_bf16 v[94:97], v[150:153], v[228:231], v[94:97]
	v_mfma_f32_16x16x32_bf16 v[90:93], v[168:171], v[228:231], v[90:93]
	v_mfma_f32_16x16x32_bf16 v[78:81], v[150:153], v[236:239], v[78:81]
	v_mfma_f32_16x16x32_bf16 v[74:77], v[168:171], v[236:239], v[74:77]
	v_mfma_f32_16x16x32_bf16 v[118:121], v[172:175], v[188:191], v[118:121]
	v_mfma_f32_16x16x32_bf16 v[114:117], v[180:183], v[188:191], v[114:117]
	v_mfma_f32_16x16x32_bf16 v[102:105], v[172:175], v[216:219], v[102:105]
	v_mfma_f32_16x16x32_bf16 v[98:101], v[180:183], v[216:219], v[98:101]
	v_mfma_f32_16x16x32_bf16 v[86:89], v[172:175], v[224:227], v[86:89]
	v_mfma_f32_16x16x32_bf16 v[82:85], v[180:183], v[224:227], v[82:85]
	v_mfma_f32_16x16x32_bf16 v[70:73], v[172:175], v[232:235], v[70:73]
	v_mfma_f32_16x16x32_bf16 v[66:69], v[180:183], v[232:235], v[66:69]
	v_mfma_f32_16x16x32_bf16 v[118:121], v[176:179], v[212:215], v[118:121]
	v_mfma_f32_16x16x32_bf16 v[114:117], v[184:187], v[212:215], v[114:117]
	v_mfma_f32_16x16x32_bf16 v[102:105], v[176:179], v[220:223], v[102:105]
	v_mfma_f32_16x16x32_bf16 v[98:101], v[184:187], v[220:223], v[98:101]
	v_mfma_f32_16x16x32_bf16 v[86:89], v[176:179], v[228:231], v[86:89]
	v_mfma_f32_16x16x32_bf16 v[82:85], v[184:187], v[228:231], v[82:85]
	v_mfma_f32_16x16x32_bf16 v[70:73], v[176:179], v[236:239], v[70:73]
	v_mfma_f32_16x16x32_bf16 v[66:69], v[184:187], v[236:239], v[66:69]
	s_setprio 1
	s_barrier
	s_add_i32 s55, s55, s40
	v_lshl_add_u64 v[144:145], s[28:29], 0, v[0:1]
	s_mov_b32 m0, s55
	ds_read_b128 v[188:191], v149 offset:16384
	ds_read_b128 v[212:215], v149 offset:17408
	ds_read_b128 v[216:219], v149 offset:18432
	ds_read_b128 v[220:223], v149 offset:19456
	ds_read_b128 v[224:227], v149 offset:20480
	ds_read_b128 v[228:231], v149 offset:21504
	ds_read_b128 v[232:235], v149 offset:22528
	ds_read_b128 v[236:239], v149 offset:23552
	global_load_lds_dwordx4 v[144:145], off
	s_add_i32 m0, s55, 0x2000
	s_add_u32 s56, s28, 0x20000
	v_lshl_add_u64 v[192:193], s[28:29], 0, v[130:131]
	s_addc_u32 s57, s29, 0
	s_add_i32 s55, s58, s40
	global_load_lds_dwordx4 v[192:193], off
	v_lshl_add_u64 v[240:241], s[56:57], 0, v[0:1]
	s_mov_b32 m0, s55
	v_lshl_add_u64 v[242:243], s[30:31], 0, v[132:133]
	global_load_lds_dwordx4 v[240:241], off
	v_lshl_add_u64 v[240:241], s[56:57], 0, v[130:131]
	s_add_i32 m0, s55, 0x2000
	s_nop 0
	global_load_lds_dwordx4 v[240:241], off
	v_lshl_add_u64 v[240:241], s[30:31], 0, v[134:135]
	s_mov_b32 m0, s41
	s_nop 0
	global_load_lds_dwordx4 v[240:241], off
	s_mov_b32 m0, s42
	s_nop 0
	global_load_lds_dwordx4 v[242:243], off
	s_waitcnt vmcnt(8)
	s_waitcnt lgkmcnt(0)
	s_barrier
; #define PG8_STAGE(bufoff, gbase, voff) do { _Pragma("unroll") for (int _i = 0; _i < 2; ++_i) \
;         __builtin_amdgcn_global_load_lds((const unsigned*)((const char*)(gbase) + (voff)[_i]), (PG8_LAS unsigned*)(lds + (bufoff) + ldsw + _i * 8192), 16, 0, 0); } while (0)
; #define PG8_LDA(dst, b, h) do { _Pragma("unroll") for (int m = 0; m < 4; ++m) _Pragma("unroll") for (int k = 0; k < 2; ++k) dst[m][k] = *(const PG8_LAS bf16x8*)(lds + PG8_SA(b, h) + aoff + m * 2048 + k * 1024); } while (0)
; #define PG8_LDB(dst, b, h) do { _Pragma("unroll") for (int n = 0; n < 2; ++n) _Pragma("unroll") for (int k = 0; k < 2; ++k) dst[n][k] = *(const PG8_LAS bf16x8*)(lds + PG8_SB(b, h) + boff + n * 2048 + k * 1024); } while (0)
; #define PG8_MMA(ai, bj, At, Bt) do { __builtin_amdgcn_s_setprio(1); _Pragma("unroll") for (int m = 0; m < 4; ++m) _Pragma("unroll") for (int n = 0; n < 2; ++n) _Pragma("unroll") for (int k = 0; k < 2; ++k) \
;         acc[ai][bj][m][n] = __builtin_amdgcn_mfma_f32_16x16x32_bf16(Bt[n][k], At[m][k], acc[ai][bj][m][n], 0, 0, 0); __builtin_amdgcn_s_setprio(0); } while (0)
; #define PG8_WAIT_V(n) asm volatile("s_waitcnt vmcnt(" #n ")" ::: "memory")
; #define PG8_WAIT_L(n) asm volatile("s_waitcnt lgkmcnt(" #n ")" ::: "memory")
; #define PG8_BAR __builtin_amdgcn_s_barrier()
; #define PG8_SCHED __builtin_amdgcn_sched_barrier(0)
; template <class Epi, class Sched, bool ALIGN_EPI = false, bool SP2 = false>
; __device__ __forceinline__ void gemm_phase(PG8_LAS unsigned char* lds, const Gemm g, const Sched& S, const Epi& E, int wave_in) {
;     ...
;             PG8_WAIT_V(8); PG8_WAIT_L(0); PG8_BAR; PG8_MMA(1, 0, At, B0); PG8_MMA(1, 1, At, B1); PG8_BAR; PG8_SCHED;
;             PG8_LDB(B0, 1, 0); PG8_LDB(B1, 1, 1); PG8_SCHED; PG8_LDA(At, 1, 0); PG8_STAGE(PG8_SA(0, 1), a2 + hstepA, voffA);
;             PG8_WAIT_V(8); PG8_WAIT_L(0); PG8_BAR; PG8_MMA(0, 0, At, B0); PG8_MMA(0, 1, At, B1); PG8_BAR; PG8_SCHED;
	s_setprio 0
	s_waitcnt lgkmcnt(0)
	v_mfma_f32_16x16x32_bf16 v[62:65], v[140:143], v[188:191], v[62:65]
	v_mfma_f32_16x16x32_bf16 v[58:61], v[154:157], v[188:191], v[58:61]
	v_mfma_f32_16x16x32_bf16 v[46:49], v[140:143], v[216:219], v[46:49]
	v_mfma_f32_16x16x32_bf16 v[42:45], v[154:157], v[216:219], v[42:45]
	v_mfma_f32_16x16x32_bf16 v[30:33], v[140:143], v[224:227], v[30:33]
	v_mfma_f32_16x16x32_bf16 v[26:29], v[154:157], v[224:227], v[26:29]
	v_mfma_f32_16x16x32_bf16 v[14:17], v[140:143], v[232:235], v[14:17]
	v_mfma_f32_16x16x32_bf16 v[10:13], v[154:157], v[232:235], v[10:13]
	v_mfma_f32_16x16x32_bf16 v[62:65], v[150:153], v[212:215], v[62:65]
	v_mfma_f32_16x16x32_bf16 v[58:61], v[168:171], v[212:215], v[58:61]
	v_mfma_f32_16x16x32_bf16 v[46:49], v[150:153], v[220:223], v[46:49]
	v_mfma_f32_16x16x32_bf16 v[42:45], v[168:171], v[220:223], v[42:45]
	v_mfma_f32_16x16x32_bf16 v[30:33], v[150:153], v[228:231], v[30:33]
	v_mfma_f32_16x16x32_bf16 v[26:29], v[168:171], v[228:231], v[26:29]
	v_mfma_f32_16x16x32_bf16 v[14:17], v[150:153], v[236:239], v[14:17]
	v_mfma_f32_16x16x32_bf16 v[10:13], v[168:171], v[236:239], v[10:13]
	v_mfma_f32_16x16x32_bf16 v[54:57], v[172:175], v[188:191], v[54:57]
	v_mfma_f32_16x16x32_bf16 v[50:53], v[180:183], v[188:191], v[50:53]
	v_mfma_f32_16x16x32_bf16 v[38:41], v[172:175], v[216:219], v[38:41]
	v_mfma_f32_16x16x32_bf16 v[34:37], v[180:183], v[216:219], v[34:37]
	v_mfma_f32_16x16x32_bf16 v[22:25], v[172:175], v[224:227], v[22:25]
	v_mfma_f32_16x16x32_bf16 v[18:21], v[180:183], v[224:227], v[18:21]
	v_mfma_f32_16x16x32_bf16 v[6:9], v[172:175], v[232:235], v[6:9]
	v_mfma_f32_16x16x32_bf16 v[2:5], v[180:183], v[232:235], v[2:5]
	v_mfma_f32_16x16x32_bf16 v[54:57], v[176:179], v[212:215], v[54:57]
	v_mfma_f32_16x16x32_bf16 v[50:53], v[184:187], v[212:215], v[50:53]
	v_mfma_f32_16x16x32_bf16 v[38:41], v[176:179], v[220:223], v[38:41]
	v_mfma_f32_16x16x32_bf16 v[34:37], v[184:187], v[220:223], v[34:37]
	v_mfma_f32_16x16x32_bf16 v[22:25], v[176:179], v[228:231], v[22:25]
	v_mfma_f32_16x16x32_bf16 v[18:21], v[184:187], v[228:231], v[18:21]
	v_mfma_f32_16x16x32_bf16 v[6:9], v[176:179], v[236:239], v[6:9]
	v_mfma_f32_16x16x32_bf16 v[2:5], v[184:187], v[236:239], v[2:5]
	s_setprio 1
	s_barrier
	s_add_i32 s55, 0, 0x18000
	s_add_i32 s56, 0, 0x1c000
	v_add_u32_e32 v168, s55, v147
	v_add_u32_e32 v184, s56, v147
	ds_read_b128 v[140:143], v168
	ds_read_b128 v[150:153], v168 offset:1024
	ds_read_b128 v[154:157], v168 offset:2048
	ds_read_b128 v[168:171], v168 offset:3072
	ds_read_b128 v[172:175], v184
	ds_read_b128 v[176:179], v184 offset:1024
	ds_read_b128 v[180:183], v184 offset:2048
	ds_read_b128 v[184:187], v184 offset:3072
	s_add_u32 s30, s30, 0x80000
	s_addc_u32 s31, s31, 0
	s_mov_b32 m0, s43
	v_lshl_add_u64 v[244:245], s[30:31], 0, v[134:135]
	ds_read_b128 v[188:191], v149 offset:32768
	ds_read_b128 v[212:215], v149 offset:33792
	ds_read_b128 v[216:219], v149 offset:34816
	ds_read_b128 v[220:223], v149 offset:35840
	ds_read_b128 v[224:227], v149 offset:36864
	ds_read_b128 v[228:231], v149 offset:37888
	ds_read_b128 v[232:235], v149 offset:38912
	ds_read_b128 v[236:239], v149 offset:39936
	global_load_lds_dwordx4 v[244:245], off
	v_lshl_add_u64 v[244:245], s[30:31], 0, v[132:133]
	s_mov_b32 m0, s44
	s_nop 0
	global_load_lds_dwordx4 v[244:245], off
	s_waitcnt vmcnt(8)
	s_waitcnt lgkmcnt(0)
	s_barrier
	s_setprio 0
	s_waitcnt lgkmcnt(0)
	v_mfma_f32_16x16x32_bf16 v[126:129], v[140:143], v[188:191], v[126:129]
	v_mfma_f32_16x16x32_bf16 v[122:125], v[154:157], v[188:191], v[122:125]
	v_mfma_f32_16x16x32_bf16 v[110:113], v[140:143], v[216:219], v[110:113]
	v_mfma_f32_16x16x32_bf16 v[106:109], v[154:157], v[216:219], v[106:109]
	v_mfma_f32_16x16x32_bf16 v[94:97], v[140:143], v[224:227], v[94:97]
	v_mfma_f32_16x16x32_bf16 v[90:93], v[154:157], v[224:227], v[90:93]
	v_mfma_f32_16x16x32_bf16 v[78:81], v[140:143], v[232:235], v[78:81]
	v_mfma_f32_16x16x32_bf16 v[74:77], v[154:157], v[232:235], v[74:77]
	v_mfma_f32_16x16x32_bf16 v[126:129], v[150:153], v[212:215], v[126:129]
	v_mfma_f32_16x16x32_bf16 v[122:125], v[168:171], v[212:215], v[122:125]
	v_mfma_f32_16x16x32_bf16 v[110:113], v[150:153], v[220:223], v[110:113]
	v_mfma_f32_16x16x32_bf16 v[106:109], v[168:171], v[220:223], v[106:109]
	v_mfma_f32_16x16x32_bf16 v[94:97], v[150:153], v[228:231], v[94:97]
	v_mfma_f32_16x16x32_bf16 v[90:93], v[168:171], v[228:231], v[90:93]
	v_mfma_f32_16x16x32_bf16 v[78:81], v[150:153], v[236:239], v[78:81]
	v_mfma_f32_16x16x32_bf16 v[74:77], v[168:171], v[236:239], v[74:77]
	v_mfma_f32_16x16x32_bf16 v[118:121], v[172:175], v[188:191], v[118:121]
	v_mfma_f32_16x16x32_bf16 v[114:117], v[180:183], v[188:191], v[114:117]
	v_mfma_f32_16x16x32_bf16 v[102:105], v[172:175], v[216:219], v[102:105]
	v_mfma_f32_16x16x32_bf16 v[98:101], v[180:183], v[216:219], v[98:101]
	v_mfma_f32_16x16x32_bf16 v[86:89], v[172:175], v[224:227], v[86:89]
	v_mfma_f32_16x16x32_bf16 v[82:85], v[180:183], v[224:227], v[82:85]
	v_mfma_f32_16x16x32_bf16 v[70:73], v[172:175], v[232:235], v[70:73]
	v_mfma_f32_16x16x32_bf16 v[66:69], v[180:183], v[232:235], v[66:69]
	v_mfma_f32_16x16x32_bf16 v[118:121], v[176:179], v[212:215], v[118:121]
	v_mfma_f32_16x16x32_bf16 v[114:117], v[184:187], v[212:215], v[114:117]
	v_mfma_f32_16x16x32_bf16 v[102:105], v[176:179], v[220:223], v[102:105]
	v_mfma_f32_16x16x32_bf16 v[98:101], v[184:187], v[220:223], v[98:101]
	v_mfma_f32_16x16x32_bf16 v[86:89], v[176:179], v[228:231], v[86:89]
	v_mfma_f32_16x16x32_bf16 v[82:85], v[184:187], v[228:231], v[82:85]
	v_mfma_f32_16x16x32_bf16 v[70:73], v[176:179], v[236:239], v[70:73]
	v_mfma_f32_16x16x32_bf16 v[66:69], v[184:187], v[236:239], v[66:69]
	s_setprio 1
	s_barrier
; #define PG8_STAGE(bufoff, gbase, voff) do { _Pragma("unroll") for (int _i = 0; _i < 2; ++_i) \
;         __builtin_amdgcn_global_load_lds((const unsigned*)((const char*)(gbase) + (voff)[_i]), (PG8_LAS unsigned*)(lds + (bufoff) + ldsw + _i * 8192), 16, 0, 0); } while (0)
; #define PG8_LDA(dst, b, h) do { _Pragma("unroll") for (int m = 0; m < 4; ++m) _Pragma("unroll") for (int k = 0; k < 2; ++k) dst[m][k] = *(const PG8_LAS bf16x8*)(lds + PG8_SA(b, h) + aoff + m * 2048 + k * 1024); } while (0)
; #define PG8_MMA(ai, bj, At, Bt) do { __builtin_amdgcn_s_setprio(1); _Pragma("unroll") for (int m = 0; m < 4; ++m) _Pragma("unroll") for (int n = 0; n < 2; ++n) _Pragma("unroll") for (int k = 0; k < 2; ++k) \
;         acc[ai][bj][m][n] = __builtin_amdgcn_mfma_f32_16x16x32_bf16(Bt[n][k], At[m][k], acc[ai][bj][m][n], 0, 0, 0); __builtin_amdgcn_s_setprio(0); } while (0)
; #define PG8_WAIT_V(n) asm volatile("s_waitcnt vmcnt(" #n ")" ::: "memory")
; #define PG8_WAIT_L(n) asm volatile("s_waitcnt lgkmcnt(" #n ")" ::: "memory")
; #define PG8_BAR __builtin_amdgcn_s_barrier()
; #define PG8_SCHED __builtin_amdgcn_sched_barrier(0)
; template <class Epi, class Sched, bool ALIGN_EPI = false, bool SP2 = false>
; __device__ __forceinline__ void gemm_phase(PG8_LAS unsigned char* lds, const Gemm g, const Sched& S, const Epi& E, int wave_in) {
;     ...
;         for (int t = 0; t < nt; t += 2) {
;             const bool last = (t == nt - 2);
;             const char* a1 = cA + (size_t)(t + 1) * kstep;
;             const char* a2 = last ? nA : cA + (size_t)(t + 2) * kstep; const char* b2 = last ? nB : cB + (size_t)(t + 2) * kstep;
;     ...
;             PG8_LDA(At, 1, 1); PG8_STAGE(PG8_SB(1, 0), b3, voffB); PG8_STAGE(PG8_SB(1, 1), b3 + hstep, voffB); PG8_STAGE(PG8_SA(1, 0), a3, voffA);
;             PG8_WAIT_V(8); PG8_WAIT_L(0); PG8_BAR; PG8_MMA(1, 0, At, B0); PG8_MMA(1, 1, At, B1); PG8_BAR; PG8_SCHED;
	s_add_i32 s30, s55, s40
	v_lshl_add_u64 v[144:145], v[144:145], 0, s[84:85]
	s_mov_b32 m0, s30
	ds_read_b128 v[188:191], v149 offset:49152
	ds_read_b128 v[212:215], v149 offset:50176
	ds_read_b128 v[216:219], v149 offset:51200
	ds_read_b128 v[220:223], v149 offset:52224
	ds_read_b128 v[224:227], v149 offset:53248
	ds_read_b128 v[228:231], v149 offset:54272
	ds_read_b128 v[232:235], v149 offset:55296
	ds_read_b128 v[236:239], v149 offset:56320
	global_load_lds_dwordx4 v[144:145], off
	s_add_i32 m0, s30, 0x2000
	s_add_u32 s28, s28, 0x20080
	v_lshl_add_u64 v[144:145], v[192:193], 0, s[84:85]
	s_addc_u32 s29, s29, 0
	s_add_i32 s30, s56, s40
	global_load_lds_dwordx4 v[144:145], off
	v_lshl_add_u64 v[144:145], s[28:29], 0, v[0:1]
	s_mov_b32 m0, s30
	s_nop 0
	global_load_lds_dwordx4 v[144:145], off
	v_lshl_add_u64 v[144:145], s[28:29], 0, v[130:131]
	s_add_i32 m0, s30, 0x2000
	s_nop 0
	global_load_lds_dwordx4 v[144:145], off
	v_lshl_add_u64 v[144:145], v[240:241], 0, s[84:85]
	s_mov_b32 m0, s45
	s_nop 0
	global_load_lds_dwordx4 v[144:145], off
	v_lshl_add_u64 v[144:145], v[242:243], 0, s[84:85]
	s_mov_b32 m0, s46
	s_nop 0
	global_load_lds_dwordx4 v[144:145], off
	s_waitcnt vmcnt(8)
	s_waitcnt lgkmcnt(0)
	s_barrier
	s_setprio 0
	s_waitcnt lgkmcnt(0)
	v_mfma_f32_16x16x32_bf16 v[62:65], v[140:143], v[188:191], v[62:65]
	v_mfma_f32_16x16x32_bf16 v[58:61], v[154:157], v[188:191], v[58:61]
	v_mfma_f32_16x16x32_bf16 v[46:49], v[140:143], v[216:219], v[46:49]
	v_mfma_f32_16x16x32_bf16 v[42:45], v[154:157], v[216:219], v[42:45]
	v_mfma_f32_16x16x32_bf16 v[30:33], v[140:143], v[224:227], v[30:33]
	v_mfma_f32_16x16x32_bf16 v[26:29], v[154:157], v[224:227], v[26:29]
	v_mfma_f32_16x16x32_bf16 v[14:17], v[140:143], v[232:235], v[14:17]
	v_mfma_f32_16x16x32_bf16 v[10:13], v[154:157], v[232:235], v[10:13]
	v_mfma_f32_16x16x32_bf16 v[62:65], v[150:153], v[212:215], v[62:65]
	v_mfma_f32_16x16x32_bf16 v[58:61], v[168:171], v[212:215], v[58:61]
	v_mfma_f32_16x16x32_bf16 v[46:49], v[150:153], v[220:223], v[46:49]
	v_mfma_f32_16x16x32_bf16 v[42:45], v[168:171], v[220:223], v[42:45]
	v_mfma_f32_16x16x32_bf16 v[30:33], v[150:153], v[228:231], v[30:33]
	v_mfma_f32_16x16x32_bf16 v[26:29], v[168:171], v[228:231], v[26:29]
	v_mfma_f32_16x16x32_bf16 v[14:17], v[150:153], v[236:239], v[14:17]
	v_mfma_f32_16x16x32_bf16 v[10:13], v[168:171], v[236:239], v[10:13]
	v_mfma_f32_16x16x32_bf16 v[54:57], v[172:175], v[188:191], v[54:57]
	v_mfma_f32_16x16x32_bf16 v[50:53], v[180:183], v[188:191], v[50:53]
	v_mfma_f32_16x16x32_bf16 v[38:41], v[172:175], v[216:219], v[38:41]
	v_mfma_f32_16x16x32_bf16 v[34:37], v[180:183], v[216:219], v[34:37]
	v_mfma_f32_16x16x32_bf16 v[22:25], v[172:175], v[224:227], v[22:25]
	v_mfma_f32_16x16x32_bf16 v[18:21], v[180:183], v[224:227], v[18:21]
	v_mfma_f32_16x16x32_bf16 v[6:9], v[172:175], v[232:235], v[6:9]
	v_mfma_f32_16x16x32_bf16 v[2:5], v[180:183], v[232:235], v[2:5]
	v_mfma_f32_16x16x32_bf16 v[54:57], v[176:179], v[212:215], v[54:57]
	v_mfma_f32_16x16x32_bf16 v[50:53], v[184:187], v[212:215], v[50:53]
	v_mfma_f32_16x16x32_bf16 v[38:41], v[176:179], v[220:223], v[38:41]
	v_mfma_f32_16x16x32_bf16 v[34:37], v[184:187], v[220:223], v[34:37]
	v_mfma_f32_16x16x32_bf16 v[22:25], v[176:179], v[228:231], v[22:25]
	v_mfma_f32_16x16x32_bf16 v[18:21], v[184:187], v[228:231], v[18:21]
	v_mfma_f32_16x16x32_bf16 v[6:9], v[176:179], v[236:239], v[6:9]
	v_mfma_f32_16x16x32_bf16 v[2:5], v[184:187], v[236:239], v[2:5]
	s_setprio 1
	s_barrier
	s_add_i32 s54, s54, 2
	s_add_u32 s26, s26, 0x100
	s_addc_u32 s27, s27, 0
	s_add_u32 s52, s52, 0x100
	s_addc_u32 s53, s53, 0
	s_cmp_gt_u32 s54, 5
	s_cbranch_scc0 .LBB0_107
	s_and_b64 vcc, exec, s[16:17]
	s_cbranch_vccz .LBB0_110
	s_barrier

; #define PG8_STAGE(bufoff, gbase, voff) do { _Pragma("unroll") for (int _i = 0; _i < 2; ++_i) \
;         __builtin_amdgcn_global_load_lds((const unsigned*)((const char*)(gbase) + (voff)[_i]), (PG8_LAS unsigned*)(lds + (bufoff) + ldsw + _i * 8192), 16, 0, 0); } while (0)
; #define PG8_LDA(dst, b, h) do { _Pragma("unroll") for (int m = 0; m < 4; ++m) _Pragma("unroll") for (int k = 0; k < 2; ++k) dst[m][k] = *(const PG8_LAS bf16x8*)(lds + PG8_SA(b, h) + aoff + m * 2048 + k * 1024); } while (0)
; #define PG8_LDB(dst, b, h) do { _Pragma("unroll") for (int n = 0; n < 2; ++n) _Pragma("unroll") for (int k = 0; k < 2; ++k) dst[n][k] = *(const PG8_LAS bf16x8*)(lds + PG8_SB(b, h) + boff + n * 2048 + k * 1024); } while (0)
; #define PG8_WAIT_V(n) asm volatile("s_waitcnt vmcnt(" #n ")" ::: "memory")
; #define PG8_WAIT_L(n) asm volatile("s_waitcnt lgkmcnt(" #n ")" ::: "memory")
; #define PG8_BAR __builtin_amdgcn_s_barrier()
; #define PG8_SCHED __builtin_amdgcn_sched_barrier(0)
; template <class Epi, class Sched, bool ALIGN_EPI = false, bool SP2 = false>
; __device__ __forceinline__ void gemm_phase(PG8_LAS unsigned char* lds, const Gemm g, const Sched& S, const Epi& E, int wave_in) {
;     ...
;         const char* nA = has_next ? (const char*)g.A + (size_t)nxt.pm * tstepA : cA; const char* nB = has_next ? (const char*)g.Bt + (size_t)nxt.pn * tstep : cB;
;         for (int t = 0; t < nt; t += 2) {
;             const bool last = (t == nt - 2);
;             const char* a1 = cA + (size_t)(t + 1) * kstep;
;             const char* a2 = last ? nA : cA + (size_t)(t + 2) * kstep; const char* b2 = last ? nB : cB + (size_t)(t + 2) * kstep;
;             const char* a3 = a2 + kstep; const char* b3 = b2 + kstep;
;             if (last && has_next) S.a_ready(nxt);
;             if constexpr (SP2) {
;             PG8_LDB(B0, 0, 0); PG8_LDB(B1, 0, 1); PG8_SCHED; PG8_LDA(At, 0, 0); PG8_STAGE(PG8_SA(1, 1), a1 + hstepA, voffA);
;             PG8_WAIT_V(8); PG8_WAIT_L(0); PG8_BAR; PG8_MMA(0, 0, At, B0); PG8_MMA(0, 1, At, B1); PG8_BAR; PG8_SCHED;
;             PG8_LDA(At, 0, 1); PG8_STAGE(PG8_SB(0, 0), b2, voffB); PG8_STAGE(PG8_SB(0, 1), b2 + hstep, voffB); PG8_STAGE(PG8_SA(0, 0), a2, voffA);
;             PG8_WAIT_V(8); PG8_WAIT_L(0); PG8_BAR; PG8_MMA(1, 0, At, B0); PG8_MMA(1, 1, At, B1); PG8_BAR; PG8_SCHED;
.LBB0_128:
	s_add_u32 s24, s22, 0xfffe0080
	s_addc_u32 s25, s23, -1
	s_add_i32 s47, 0, 0x10000
	s_cmp_eq_u32 s46, 4
	s_cselect_b32 s27, s17, s25
	s_cselect_b32 s26, s42, s24
	s_cselect_b32 s25, s11, s45
	s_cselect_b32 s24, s43, s44
	s_add_i32 s50, 0, 0x14000
	v_add_u32_e32 v70, s47, v171
	v_add_u32_e32 v156, s50, v171
	ds_read_b128 v[58:61], v70
	ds_read_b128 v[62:65], v70 offset:1024
	ds_read_b128 v[66:69], v70 offset:2048
	ds_read_b128 v[70:73], v70 offset:3072
	ds_read_b128 v[174:177], v156
	ds_read_b128 v[178:181], v156 offset:1024
	ds_read_b128 v[182:185], v156 offset:2048
	ds_read_b128 v[186:189], v156 offset:3072
	v_lshl_add_u64 v[156:157], s[22:23], 0, v[152:153]
	s_add_i32 m0, s31, 0xc000
	ds_read_b128 v[190:193], v173
	ds_read_b128 v[212:215], v173 offset:1024
	ds_read_b128 v[216:219], v173 offset:2048
	ds_read_b128 v[220:223], v173 offset:3072
	ds_read_b128 v[224:227], v173 offset:4096
	ds_read_b128 v[228:231], v173 offset:5120
	ds_read_b128 v[232:235], v173 offset:6144
	ds_read_b128 v[236:239], v173 offset:7168
	global_load_lds_dwordx4 v[156:157], off
	v_lshl_add_u64 v[156:157], s[22:23], 0, v[154:155]
	s_add_i32 m0, s31, 0xe000
	s_nop 0
	global_load_lds_dwordx4 v[156:157], off
	s_waitcnt vmcnt(8)
	s_waitcnt lgkmcnt(0)
	s_barrier
	s_setprio 0
	s_waitcnt lgkmcnt(0)
	v_mfma_f32_16x16x32_bf16 v[142:145], v[58:61], v[190:193], v[142:145]
	v_mfma_f32_16x16x32_bf16 v[138:141], v[66:69], v[190:193], v[138:141]
	v_mfma_f32_16x16x32_bf16 v[126:129], v[58:61], v[216:219], v[126:129]
	v_mfma_f32_16x16x32_bf16 v[122:125], v[66:69], v[216:219], v[122:125]
	v_mfma_f32_16x16x32_bf16 v[110:113], v[58:61], v[224:227], v[110:113]
	v_mfma_f32_16x16x32_bf16 v[106:109], v[66:69], v[224:227], v[106:109]
	v_mfma_f32_16x16x32_bf16 v[94:97], v[58:61], v[232:235], v[94:97]
	v_mfma_f32_16x16x32_bf16 v[90:93], v[66:69], v[232:235], v[90:93]
	v_mfma_f32_16x16x32_bf16 v[142:145], v[62:65], v[212:215], v[142:145]
	v_mfma_f32_16x16x32_bf16 v[138:141], v[70:73], v[212:215], v[138:141]
	v_mfma_f32_16x16x32_bf16 v[126:129], v[62:65], v[220:223], v[126:129]
	v_mfma_f32_16x16x32_bf16 v[122:125], v[70:73], v[220:223], v[122:125]
	v_mfma_f32_16x16x32_bf16 v[110:113], v[62:65], v[228:231], v[110:113]
	v_mfma_f32_16x16x32_bf16 v[106:109], v[70:73], v[228:231], v[106:109]
	v_mfma_f32_16x16x32_bf16 v[94:97], v[62:65], v[236:239], v[94:97]
	v_mfma_f32_16x16x32_bf16 v[90:93], v[70:73], v[236:239], v[90:93]
	v_mfma_f32_16x16x32_bf16 v[134:137], v[174:177], v[190:193], v[134:137]
	v_mfma_f32_16x16x32_bf16 v[130:133], v[182:185], v[190:193], v[130:133]
	v_mfma_f32_16x16x32_bf16 v[118:121], v[174:177], v[216:219], v[118:121]
	v_mfma_f32_16x16x32_bf16 v[114:117], v[182:185], v[216:219], v[114:117]
	v_mfma_f32_16x16x32_bf16 v[102:105], v[174:177], v[224:227], v[102:105]
	v_mfma_f32_16x16x32_bf16 v[98:101], v[182:185], v[224:227], v[98:101]
	v_mfma_f32_16x16x32_bf16 v[86:89], v[174:177], v[232:235], v[86:89]
	v_mfma_f32_16x16x32_bf16 v[82:85], v[182:185], v[232:235], v[82:85]
	v_mfma_f32_16x16x32_bf16 v[134:137], v[178:181], v[212:215], v[134:137]
	v_mfma_f32_16x16x32_bf16 v[130:133], v[186:189], v[212:215], v[130:133]
	v_mfma_f32_16x16x32_bf16 v[118:121], v[178:181], v[220:223], v[118:121]
	v_mfma_f32_16x16x32_bf16 v[114:117], v[186:189], v[220:223], v[114:117]
	v_mfma_f32_16x16x32_bf16 v[102:105], v[178:181], v[228:231], v[102:105]
	v_mfma_f32_16x16x32_bf16 v[98:101], v[186:189], v[228:231], v[98:101]
	v_mfma_f32_16x16x32_bf16 v[86:89], v[178:181], v[236:239], v[86:89]
	v_mfma_f32_16x16x32_bf16 v[82:85], v[186:189], v[236:239], v[82:85]
	s_setprio 1
	s_barrier
	s_add_i32 s47, s47, s30
	v_lshl_add_u64 v[156:157], s[24:25], 0, v[0:1]
	s_mov_b32 m0, s47
	ds_read_b128 v[190:193], v173 offset:16384
	ds_read_b128 v[212:215], v173 offset:17408
	ds_read_b128 v[216:219], v173 offset:18432
	ds_read_b128 v[220:223], v173 offset:19456
	ds_read_b128 v[224:227], v173 offset:20480
	ds_read_b128 v[228:231], v173 offset:21504
	ds_read_b128 v[232:235], v173 offset:22528
	ds_read_b128 v[236:239], v173 offset:23552
	global_load_lds_dwordx4 v[156:157], off
	s_add_i32 m0, s47, 0x2000
	s_add_u32 s48, s24, 0x20000
	v_lshl_add_u64 v[168:169], s[24:25], 0, v[146:147]
	s_addc_u32 s49, s25, 0
	s_add_i32 s47, s50, s30
	global_load_lds_dwordx4 v[168:169], off
	v_lshl_add_u64 v[240:241], s[48:49], 0, v[0:1]
	s_mov_b32 m0, s47
	v_lshl_add_u64 v[242:243], s[26:27], 0, v[148:149]
	global_load_lds_dwordx4 v[240:241], off
	v_lshl_add_u64 v[240:241], s[48:49], 0, v[146:147]
	s_add_i32 m0, s47, 0x2000
	s_nop 0
	global_load_lds_dwordx4 v[240:241], off
	v_lshl_add_u64 v[240:241], s[26:27], 0, v[150:151]
	s_mov_b32 m0, s31
	s_nop 0
	global_load_lds_dwordx4 v[240:241], off
	s_mov_b32 m0, s34
	s_nop 0
	global_load_lds_dwordx4 v[242:243], off
	s_waitcnt vmcnt(8)
	s_waitcnt lgkmcnt(0)
	s_barrier
; #define PG8_STAGE(bufoff, gbase, voff) do { _Pragma("unroll") for (int _i = 0; _i < 2; ++_i) \
;         __builtin_amdgcn_global_load_lds((const unsigned*)((const char*)(gbase) + (voff)[_i]), (PG8_LAS unsigned*)(lds + (bufoff) + ldsw + _i * 8192), 16, 0, 0); } while (0)
; #define PG8_LDA(dst, b, h) do { _Pragma("unroll") for (int m = 0; m < 4; ++m) _Pragma("unroll") for (int k = 0; k < 2; ++k) dst[m][k] = *(const PG8_LAS bf16x8*)(lds + PG8_SA(b, h) + aoff + m * 2048 + k * 1024); } while (0)
; #define PG8_LDB(dst, b, h) do { _Pragma("unroll") for (int n = 0; n < 2; ++n) _Pragma("unroll") for (int k = 0; k < 2; ++k) dst[n][k] = *(const PG8_LAS bf16x8*)(lds + PG8_SB(b, h) + boff + n * 2048 + k * 1024); } while (0)
; #define PG8_MMA(ai, bj, At, Bt) do { __builtin_amdgcn_s_setprio(1); _Pragma("unroll") for (int m = 0; m < 4; ++m) _Pragma("unroll") for (int n = 0; n < 2; ++n) _Pragma("unroll") for (int k = 0; k < 2; ++k) \
;         acc[ai][bj][m][n] = __builtin_amdgcn_mfma_f32_16x16x32_bf16(Bt[n][k], At[m][k], acc[ai][bj][m][n], 0, 0, 0); __builtin_amdgcn_s_setprio(0); } while (0)
; #define PG8_WAIT_V(n) asm volatile("s_waitcnt vmcnt(" #n ")" ::: "memory")
; #define PG8_WAIT_L(n) asm volatile("s_waitcnt lgkmcnt(" #n ")" ::: "memory")
; #define PG8_BAR __builtin_amdgcn_s_barrier()
; #define PG8_SCHED __builtin_amdgcn_sched_barrier(0)
; template <class Epi, class Sched, bool ALIGN_EPI = false, bool SP2 = false>
; __device__ __forceinline__ void gemm_phase(PG8_LAS unsigned char* lds, const Gemm g, const Sched& S, const Epi& E, int wave_in) {
;     ...
;             PG8_WAIT_V(8); PG8_WAIT_L(0); PG8_BAR; PG8_MMA(1, 0, At, B0); PG8_MMA(1, 1, At, B1); PG8_BAR; PG8_SCHED;
;             PG8_LDB(B0, 1, 0); PG8_LDB(B1, 1, 1); PG8_SCHED; PG8_LDA(At, 1, 0); PG8_STAGE(PG8_SA(0, 1), a2 + hstepA, voffA);
;             PG8_WAIT_V(8); PG8_WAIT_L(0); PG8_BAR; PG8_MMA(0, 0, At, B0); PG8_MMA(0, 1, At, B1); PG8_BAR; PG8_SCHED;
	s_setprio 0
	s_waitcnt lgkmcnt(0)
	v_mfma_f32_16x16x32_bf16 v[78:81], v[58:61], v[190:193], v[78:81]
	v_mfma_f32_16x16x32_bf16 v[74:77], v[66:69], v[190:193], v[74:77]
	v_mfma_f32_16x16x32_bf16 v[46:49], v[58:61], v[216:219], v[46:49]
	v_mfma_f32_16x16x32_bf16 v[42:45], v[66:69], v[216:219], v[42:45]
	v_mfma_f32_16x16x32_bf16 v[30:33], v[58:61], v[224:227], v[30:33]
	v_mfma_f32_16x16x32_bf16 v[26:29], v[66:69], v[224:227], v[26:29]
	v_mfma_f32_16x16x32_bf16 v[14:17], v[58:61], v[232:235], v[14:17]
	v_mfma_f32_16x16x32_bf16 v[10:13], v[66:69], v[232:235], v[10:13]
	v_mfma_f32_16x16x32_bf16 v[78:81], v[62:65], v[212:215], v[78:81]
	v_mfma_f32_16x16x32_bf16 v[74:77], v[70:73], v[212:215], v[74:77]
	v_mfma_f32_16x16x32_bf16 v[46:49], v[62:65], v[220:223], v[46:49]
	v_mfma_f32_16x16x32_bf16 v[42:45], v[70:73], v[220:223], v[42:45]
	v_mfma_f32_16x16x32_bf16 v[30:33], v[62:65], v[228:231], v[30:33]
	v_mfma_f32_16x16x32_bf16 v[26:29], v[70:73], v[228:231], v[26:29]
	v_mfma_f32_16x16x32_bf16 v[14:17], v[62:65], v[236:239], v[14:17]
	v_mfma_f32_16x16x32_bf16 v[10:13], v[70:73], v[236:239], v[10:13]
	v_mfma_f32_16x16x32_bf16 v[54:57], v[174:177], v[190:193], v[54:57]
	v_mfma_f32_16x16x32_bf16 v[50:53], v[182:185], v[190:193], v[50:53]
	v_mfma_f32_16x16x32_bf16 v[38:41], v[174:177], v[216:219], v[38:41]
	v_mfma_f32_16x16x32_bf16 v[34:37], v[182:185], v[216:219], v[34:37]
	v_mfma_f32_16x16x32_bf16 v[22:25], v[174:177], v[224:227], v[22:25]
	v_mfma_f32_16x16x32_bf16 v[18:21], v[182:185], v[224:227], v[18:21]
	v_mfma_f32_16x16x32_bf16 v[6:9], v[174:177], v[232:235], v[6:9]
	v_mfma_f32_16x16x32_bf16 v[2:5], v[182:185], v[232:235], v[2:5]
	v_mfma_f32_16x16x32_bf16 v[54:57], v[178:181], v[212:215], v[54:57]
	v_mfma_f32_16x16x32_bf16 v[50:53], v[186:189], v[212:215], v[50:53]
	v_mfma_f32_16x16x32_bf16 v[38:41], v[178:181], v[220:223], v[38:41]
	v_mfma_f32_16x16x32_bf16 v[34:37], v[186:189], v[220:223], v[34:37]
	v_mfma_f32_16x16x32_bf16 v[22:25], v[178:181], v[228:231], v[22:25]
	v_mfma_f32_16x16x32_bf16 v[18:21], v[186:189], v[228:231], v[18:21]
	v_mfma_f32_16x16x32_bf16 v[6:9], v[178:181], v[236:239], v[6:9]
	v_mfma_f32_16x16x32_bf16 v[2:5], v[186:189], v[236:239], v[2:5]
	s_setprio 1
	s_barrier
	s_add_i32 s47, 0, 0x18000
	s_add_i32 s48, 0, 0x1c000
	v_add_u32_e32 v70, s47, v171
	v_add_u32_e32 v186, s48, v171
	ds_read_b128 v[58:61], v70
	ds_read_b128 v[62:65], v70 offset:1024
	ds_read_b128 v[66:69], v70 offset:2048
	ds_read_b128 v[70:73], v70 offset:3072
	ds_read_b128 v[174:177], v186
	ds_read_b128 v[178:181], v186 offset:1024
	ds_read_b128 v[182:185], v186 offset:2048
	ds_read_b128 v[186:189], v186 offset:3072
	s_add_u32 s26, s26, 0x20000
	s_addc_u32 s27, s27, 0
	s_mov_b32 m0, s35
	v_lshl_add_u64 v[244:245], s[26:27], 0, v[150:151]
	ds_read_b128 v[190:193], v173 offset:32768
	ds_read_b128 v[212:215], v173 offset:33792
	ds_read_b128 v[216:219], v173 offset:34816
	ds_read_b128 v[220:223], v173 offset:35840
	ds_read_b128 v[224:227], v173 offset:36864
	ds_read_b128 v[228:231], v173 offset:37888
	ds_read_b128 v[232:235], v173 offset:38912
	ds_read_b128 v[236:239], v173 offset:39936
	global_load_lds_dwordx4 v[244:245], off
	v_lshl_add_u64 v[244:245], s[26:27], 0, v[148:149]
	s_mov_b32 m0, s36
	s_nop 0
	global_load_lds_dwordx4 v[244:245], off
	s_waitcnt vmcnt(8)
	s_waitcnt lgkmcnt(0)
	s_barrier
	s_setprio 0
	s_waitcnt lgkmcnt(0)
	v_mfma_f32_16x16x32_bf16 v[142:145], v[58:61], v[190:193], v[142:145]
	v_mfma_f32_16x16x32_bf16 v[138:141], v[66:69], v[190:193], v[138:141]
	v_mfma_f32_16x16x32_bf16 v[126:129], v[58:61], v[216:219], v[126:129]
	v_mfma_f32_16x16x32_bf16 v[122:125], v[66:69], v[216:219], v[122:125]
	v_mfma_f32_16x16x32_bf16 v[110:113], v[58:61], v[224:227], v[110:113]
	v_mfma_f32_16x16x32_bf16 v[106:109], v[66:69], v[224:227], v[106:109]
	v_mfma_f32_16x16x32_bf16 v[94:97], v[58:61], v[232:235], v[94:97]
	v_mfma_f32_16x16x32_bf16 v[90:93], v[66:69], v[232:235], v[90:93]
	v_mfma_f32_16x16x32_bf16 v[142:145], v[62:65], v[212:215], v[142:145]
	v_mfma_f32_16x16x32_bf16 v[138:141], v[70:73], v[212:215], v[138:141]
	v_mfma_f32_16x16x32_bf16 v[126:129], v[62:65], v[220:223], v[126:129]
	v_mfma_f32_16x16x32_bf16 v[122:125], v[70:73], v[220:223], v[122:125]
	v_mfma_f32_16x16x32_bf16 v[110:113], v[62:65], v[228:231], v[110:113]
	v_mfma_f32_16x16x32_bf16 v[106:109], v[70:73], v[228:231], v[106:109]
	v_mfma_f32_16x16x32_bf16 v[94:97], v[62:65], v[236:239], v[94:97]
	v_mfma_f32_16x16x32_bf16 v[90:93], v[70:73], v[236:239], v[90:93]
	v_mfma_f32_16x16x32_bf16 v[134:137], v[174:177], v[190:193], v[134:137]
	v_mfma_f32_16x16x32_bf16 v[130:133], v[182:185], v[190:193], v[130:133]
	v_mfma_f32_16x16x32_bf16 v[118:121], v[174:177], v[216:219], v[118:121]
	v_mfma_f32_16x16x32_bf16 v[114:117], v[182:185], v[216:219], v[114:117]
	v_mfma_f32_16x16x32_bf16 v[102:105], v[174:177], v[224:227], v[102:105]
	v_mfma_f32_16x16x32_bf16 v[98:101], v[182:185], v[224:227], v[98:101]
	v_mfma_f32_16x16x32_bf16 v[86:89], v[174:177], v[232:235], v[86:89]
	v_mfma_f32_16x16x32_bf16 v[82:85], v[182:185], v[232:235], v[82:85]
	v_mfma_f32_16x16x32_bf16 v[134:137], v[178:181], v[212:215], v[134:137]
	v_mfma_f32_16x16x32_bf16 v[130:133], v[186:189], v[212:215], v[130:133]
	v_mfma_f32_16x16x32_bf16 v[118:121], v[178:181], v[220:223], v[118:121]
	v_mfma_f32_16x16x32_bf16 v[114:117], v[186:189], v[220:223], v[114:117]
	v_mfma_f32_16x16x32_bf16 v[102:105], v[178:181], v[228:231], v[102:105]
	v_mfma_f32_16x16x32_bf16 v[98:101], v[186:189], v[228:231], v[98:101]
	v_mfma_f32_16x16x32_bf16 v[86:89], v[178:181], v[236:239], v[86:89]
	v_mfma_f32_16x16x32_bf16 v[82:85], v[186:189], v[236:239], v[82:85]
	s_setprio 1
	s_barrier
; #define PG8_STAGE(bufoff, gbase, voff) do { _Pragma("unroll") for (int _i = 0; _i < 2; ++_i) \
;         __builtin_amdgcn_global_load_lds((const unsigned*)((const char*)(gbase) + (voff)[_i]), (PG8_LAS unsigned*)(lds + (bufoff) + ldsw + _i * 8192), 16, 0, 0); } while (0)
; #define PG8_LDA(dst, b, h) do { _Pragma("unroll") for (int m = 0; m < 4; ++m) _Pragma("unroll") for (int k = 0; k < 2; ++k) dst[m][k] = *(const PG8_LAS bf16x8*)(lds + PG8_SA(b, h) + aoff + m * 2048 + k * 1024); } while (0)
; #define PG8_MMA(ai, bj, At, Bt) do { __builtin_amdgcn_s_setprio(1); _Pragma("unroll") for (int m = 0; m < 4; ++m) _Pragma("unroll") for (int n = 0; n < 2; ++n) _Pragma("unroll") for (int k = 0; k < 2; ++k) \
;         acc[ai][bj][m][n] = __builtin_amdgcn_mfma_f32_16x16x32_bf16(Bt[n][k], At[m][k], acc[ai][bj][m][n], 0, 0, 0); __builtin_amdgcn_s_setprio(0); } while (0)
; #define PG8_WAIT_V(n) asm volatile("s_waitcnt vmcnt(" #n ")" ::: "memory")
; #define PG8_WAIT_L(n) asm volatile("s_waitcnt lgkmcnt(" #n ")" ::: "memory")
; #define PG8_BAR __builtin_amdgcn_s_barrier()
; #define PG8_SCHED __builtin_amdgcn_sched_barrier(0)
; template <class Epi, class Sched, bool ALIGN_EPI = false, bool SP2 = false>
; __device__ __forceinline__ void gemm_phase(PG8_LAS unsigned char* lds, const Gemm g, const Sched& S, const Epi& E, int wave_in) {
;     ...
;         for (int t = 0; t < nt; t += 2) {
;             const bool last = (t == nt - 2);
;             const char* a1 = cA + (size_t)(t + 1) * kstep;
;             const char* a2 = last ? nA : cA + (size_t)(t + 2) * kstep; const char* b2 = last ? nB : cB + (size_t)(t + 2) * kstep;
;     ...
;             PG8_LDA(At, 1, 1); PG8_STAGE(PG8_SB(1, 0), b3, voffB); PG8_STAGE(PG8_SB(1, 1), b3 + hstep, voffB); PG8_STAGE(PG8_SA(1, 0), a3, voffA);
;             PG8_WAIT_V(8); PG8_WAIT_L(0); PG8_BAR; PG8_MMA(1, 0, At, B0); PG8_MMA(1, 1, At, B1); PG8_BAR; PG8_SCHED;
	s_add_i32 s26, s47, s30
	v_lshl_add_u64 v[156:157], v[156:157], 0, s[84:85]
	s_mov_b32 m0, s26
	ds_read_b128 v[190:193], v173 offset:49152
	ds_read_b128 v[212:215], v173 offset:50176
	ds_read_b128 v[216:219], v173 offset:51200
	ds_read_b128 v[220:223], v173 offset:52224
	ds_read_b128 v[224:227], v173 offset:53248
	ds_read_b128 v[228:231], v173 offset:54272
	ds_read_b128 v[232:235], v173 offset:55296
	ds_read_b128 v[236:239], v173 offset:56320
	global_load_lds_dwordx4 v[156:157], off
	s_add_i32 m0, s26, 0x2000
	s_add_u32 s24, s24, 0x20080
	v_lshl_add_u64 v[156:157], v[168:169], 0, s[84:85]
	s_addc_u32 s25, s25, 0
	s_add_i32 s26, s48, s30
	global_load_lds_dwordx4 v[156:157], off
	v_lshl_add_u64 v[156:157], s[24:25], 0, v[0:1]
	s_mov_b32 m0, s26
	s_nop 0
	global_load_lds_dwordx4 v[156:157], off
	v_lshl_add_u64 v[156:157], s[24:25], 0, v[146:147]
	s_add_i32 m0, s26, 0x2000
	s_nop 0
	global_load_lds_dwordx4 v[156:157], off
	v_lshl_add_u64 v[156:157], v[240:241], 0, s[84:85]
	s_mov_b32 m0, s37
	s_nop 0
	global_load_lds_dwordx4 v[156:157], off
	v_lshl_add_u64 v[156:157], v[242:243], 0, s[84:85]
	s_mov_b32 m0, s38
	s_nop 0
	global_load_lds_dwordx4 v[156:157], off
	s_waitcnt vmcnt(8)
	s_waitcnt lgkmcnt(0)
	s_barrier
	s_setprio 0
	s_waitcnt lgkmcnt(0)
	v_mfma_f32_16x16x32_bf16 v[78:81], v[58:61], v[190:193], v[78:81]
	v_mfma_f32_16x16x32_bf16 v[74:77], v[66:69], v[190:193], v[74:77]
	v_mfma_f32_16x16x32_bf16 v[46:49], v[58:61], v[216:219], v[46:49]
	v_mfma_f32_16x16x32_bf16 v[42:45], v[66:69], v[216:219], v[42:45]
	v_mfma_f32_16x16x32_bf16 v[30:33], v[58:61], v[224:227], v[30:33]
	v_mfma_f32_16x16x32_bf16 v[26:29], v[66:69], v[224:227], v[26:29]
	v_mfma_f32_16x16x32_bf16 v[14:17], v[58:61], v[232:235], v[14:17]
	v_mfma_f32_16x16x32_bf16 v[10:13], v[66:69], v[232:235], v[10:13]
	v_mfma_f32_16x16x32_bf16 v[78:81], v[62:65], v[212:215], v[78:81]
	v_mfma_f32_16x16x32_bf16 v[74:77], v[70:73], v[212:215], v[74:77]
	v_mfma_f32_16x16x32_bf16 v[46:49], v[62:65], v[220:223], v[46:49]
	v_mfma_f32_16x16x32_bf16 v[42:45], v[70:73], v[220:223], v[42:45]
	v_mfma_f32_16x16x32_bf16 v[30:33], v[62:65], v[228:231], v[30:33]
	v_mfma_f32_16x16x32_bf16 v[26:29], v[70:73], v[228:231], v[26:29]
	v_mfma_f32_16x16x32_bf16 v[14:17], v[62:65], v[236:239], v[14:17]
	v_mfma_f32_16x16x32_bf16 v[10:13], v[70:73], v[236:239], v[10:13]
	v_mfma_f32_16x16x32_bf16 v[54:57], v[174:177], v[190:193], v[54:57]
	v_mfma_f32_16x16x32_bf16 v[50:53], v[182:185], v[190:193], v[50:53]
	v_mfma_f32_16x16x32_bf16 v[38:41], v[174:177], v[216:219], v[38:41]
	v_mfma_f32_16x16x32_bf16 v[34:37], v[182:185], v[216:219], v[34:37]
	v_mfma_f32_16x16x32_bf16 v[22:25], v[174:177], v[224:227], v[22:25]
	v_mfma_f32_16x16x32_bf16 v[18:21], v[182:185], v[224:227], v[18:21]
	v_mfma_f32_16x16x32_bf16 v[6:9], v[174:177], v[232:235], v[6:9]
	v_mfma_f32_16x16x32_bf16 v[2:5], v[182:185], v[232:235], v[2:5]
	v_mfma_f32_16x16x32_bf16 v[54:57], v[178:181], v[212:215], v[54:57]
	v_mfma_f32_16x16x32_bf16 v[50:53], v[186:189], v[212:215], v[50:53]
	v_mfma_f32_16x16x32_bf16 v[38:41], v[178:181], v[220:223], v[38:41]
	v_mfma_f32_16x16x32_bf16 v[34:37], v[186:189], v[220:223], v[34:37]
	v_mfma_f32_16x16x32_bf16 v[22:25], v[178:181], v[228:231], v[22:25]
	v_mfma_f32_16x16x32_bf16 v[18:21], v[186:189], v[228:231], v[18:21]
	v_mfma_f32_16x16x32_bf16 v[6:9], v[178:181], v[236:239], v[6:9]
	v_mfma_f32_16x16x32_bf16 v[2:5], v[186:189], v[236:239], v[2:5]
	s_setprio 1
	s_barrier
	s_add_i32 s46, s46, 2
	s_add_u32 s22, s22, 0x100
	s_addc_u32 s23, s23, 0
	s_add_u32 s44, s44, 0x100
	s_addc_u32 s45, s45, 0
	s_cmp_gt_u32 s46, 5
	s_cbranch_scc0 .LBB0_128
	s_and_b64 vcc, exec, s[8:9]
	v_readlane_b32 s26, v254, 6
	v_readlane_b32 s27, v254, 7
	s_cbranch_vccz .LBB0_131
	s_barrier

; #define PG8_STAGE(bufoff, gbase, voff) do { _Pragma("unroll") for (int _i = 0; _i < 2; ++_i) \
;         __builtin_amdgcn_global_load_lds((const unsigned*)((const char*)(gbase) + (voff)[_i]), (PG8_LAS unsigned*)(lds + (bufoff) + ldsw + _i * 8192), 16, 0, 0); } while (0)
; #define PG8_LDA(dst, b, h) do { _Pragma("unroll") for (int m = 0; m < 4; ++m) _Pragma("unroll") for (int k = 0; k < 2; ++k) dst[m][k] = *(const PG8_LAS bf16x8*)(lds + PG8_SA(b, h) + aoff + m * 2048 + k * 1024); } while (0)
; #define PG8_LDB(dst, b, h) do { _Pragma("unroll") for (int n = 0; n < 2; ++n) _Pragma("unroll") for (int k = 0; k < 2; ++k) dst[n][k] = *(const PG8_LAS bf16x8*)(lds + PG8_SB(b, h) + boff + n * 2048 + k * 1024); } while (0)
; #define PG8_WAIT_V(n) asm volatile("s_waitcnt vmcnt(" #n ")" ::: "memory")
; #define PG8_WAIT_L(n) asm volatile("s_waitcnt lgkmcnt(" #n ")" ::: "memory")
; #define PG8_BAR __builtin_amdgcn_s_barrier()
; #define PG8_SCHED __builtin_amdgcn_sched_barrier(0)
; template <class Epi, class Sched, bool ALIGN_EPI = false, bool SP2 = false>
; __device__ __forceinline__ void gemm_phase(PG8_LAS unsigned char* lds, const Gemm g, const Sched& S, const Epi& E, int wave_in) {
;     ...
;         const char* nA = has_next ? (const char*)g.A + (size_t)nxt.pm * tstepA : cA; const char* nB = has_next ? (const char*)g.Bt + (size_t)nxt.pn * tstep : cB;
;         for (int t = 0; t < nt; t += 2) {
;             const bool last = (t == nt - 2);
;             const char* a1 = cA + (size_t)(t + 1) * kstep;
;             const char* a2 = last ? nA : cA + (size_t)(t + 2) * kstep; const char* b2 = last ? nB : cB + (size_t)(t + 2) * kstep;
;             const char* a3 = a2 + kstep; const char* b3 = b2 + kstep;
;             if (last && has_next) S.a_ready(nxt);
;             if constexpr (SP2) {
;             PG8_LDB(B0, 0, 0); PG8_LDB(B1, 0, 1); PG8_SCHED; PG8_LDA(At, 0, 0); PG8_STAGE(PG8_SA(1, 1), a1 + hstepA, voffA);
;             PG8_WAIT_V(8); PG8_WAIT_L(0); PG8_BAR; PG8_MMA(0, 0, At, B0); PG8_MMA(0, 1, At, B1); PG8_BAR; PG8_SCHED;
;             PG8_LDA(At, 0, 1); PG8_STAGE(PG8_SB(0, 0), b2, voffB); PG8_STAGE(PG8_SB(0, 1), b2 + hstep, voffB); PG8_STAGE(PG8_SA(0, 0), a2, voffA);
;             PG8_WAIT_V(8); PG8_WAIT_L(0); PG8_BAR; PG8_MMA(1, 0, At, B0); PG8_MMA(1, 1, At, B1); PG8_BAR; PG8_SCHED;
.LBB0_277:
	s_add_u32 s2, s0, 0xfff80080
	s_addc_u32 s3, s1, -1
	s_add_i32 s41, 0, 0x10000
	s_cmp_eq_u32 s40, 28
	s_cselect_b32 s5, s19, s3
	s_cselect_b32 s4, s36, s2
	s_cselect_b32 s3, s17, s39
	s_cselect_b32 s2, s37, s38
	s_add_i32 s44, 0, 0x14000
	v_add_u32_e32 v46, s41, v181
	v_add_u32_e32 v156, s44, v181
	ds_read_b128 v[26:29], v46
	ds_read_b128 v[30:33], v46 offset:1024
	ds_read_b128 v[42:45], v46 offset:2048
	ds_read_b128 v[46:49], v46 offset:3072
	ds_read_b128 v[168:171], v156
	ds_read_b128 v[172:175], v156 offset:1024
	ds_read_b128 v[176:179], v156 offset:2048
	ds_read_b128 v[184:187], v156 offset:3072
	v_lshl_add_u64 v[156:157], s[0:1], 0, v[152:153]
	s_add_i32 m0, s25, 0xc000
	ds_read_b128 v[188:191], v183
	ds_read_b128 v[212:215], v183 offset:1024
	ds_read_b128 v[216:219], v183 offset:2048
	ds_read_b128 v[220:223], v183 offset:3072
	ds_read_b128 v[224:227], v183 offset:4096
	ds_read_b128 v[228:231], v183 offset:5120
	ds_read_b128 v[232:235], v183 offset:6144
	ds_read_b128 v[236:239], v183 offset:7168
	global_load_lds_dwordx4 v[156:157], off
	v_lshl_add_u64 v[156:157], s[0:1], 0, v[154:155]
	s_add_i32 m0, s25, 0xe000
	s_nop 0
	global_load_lds_dwordx4 v[156:157], off
	s_waitcnt vmcnt(8)
	s_waitcnt lgkmcnt(0)
	s_barrier
	s_setprio 0
	s_waitcnt lgkmcnt(0)
	v_mfma_f32_16x16x32_bf16 v[142:145], v[26:29], v[188:191], v[142:145]
	v_mfma_f32_16x16x32_bf16 v[138:141], v[42:45], v[188:191], v[138:141]
	v_mfma_f32_16x16x32_bf16 v[126:129], v[26:29], v[216:219], v[126:129]
	v_mfma_f32_16x16x32_bf16 v[122:125], v[42:45], v[216:219], v[122:125]
	v_mfma_f32_16x16x32_bf16 v[110:113], v[26:29], v[224:227], v[110:113]
	v_mfma_f32_16x16x32_bf16 v[106:109], v[42:45], v[224:227], v[106:109]
	v_mfma_f32_16x16x32_bf16 v[94:97], v[26:29], v[232:235], v[94:97]
	v_mfma_f32_16x16x32_bf16 v[90:93], v[42:45], v[232:235], v[90:93]
	v_mfma_f32_16x16x32_bf16 v[142:145], v[30:33], v[212:215], v[142:145]
	v_mfma_f32_16x16x32_bf16 v[138:141], v[46:49], v[212:215], v[138:141]
	v_mfma_f32_16x16x32_bf16 v[126:129], v[30:33], v[220:223], v[126:129]
	v_mfma_f32_16x16x32_bf16 v[122:125], v[46:49], v[220:223], v[122:125]
	v_mfma_f32_16x16x32_bf16 v[110:113], v[30:33], v[228:231], v[110:113]
	v_mfma_f32_16x16x32_bf16 v[106:109], v[46:49], v[228:231], v[106:109]
	v_mfma_f32_16x16x32_bf16 v[94:97], v[30:33], v[236:239], v[94:97]
	v_mfma_f32_16x16x32_bf16 v[90:93], v[46:49], v[236:239], v[90:93]
	v_mfma_f32_16x16x32_bf16 v[134:137], v[168:171], v[188:191], v[134:137]
	v_mfma_f32_16x16x32_bf16 v[130:133], v[176:179], v[188:191], v[130:133]
	v_mfma_f32_16x16x32_bf16 v[118:121], v[168:171], v[216:219], v[118:121]
	v_mfma_f32_16x16x32_bf16 v[114:117], v[176:179], v[216:219], v[114:117]
	v_mfma_f32_16x16x32_bf16 v[102:105], v[168:171], v[224:227], v[102:105]
	v_mfma_f32_16x16x32_bf16 v[98:101], v[176:179], v[224:227], v[98:101]
	v_mfma_f32_16x16x32_bf16 v[86:89], v[168:171], v[232:235], v[86:89]
	v_mfma_f32_16x16x32_bf16 v[82:85], v[176:179], v[232:235], v[82:85]
	v_mfma_f32_16x16x32_bf16 v[134:137], v[172:175], v[212:215], v[134:137]
	v_mfma_f32_16x16x32_bf16 v[130:133], v[184:187], v[212:215], v[130:133]
	v_mfma_f32_16x16x32_bf16 v[118:121], v[172:175], v[220:223], v[118:121]
	v_mfma_f32_16x16x32_bf16 v[114:117], v[184:187], v[220:223], v[114:117]
	v_mfma_f32_16x16x32_bf16 v[102:105], v[172:175], v[228:231], v[102:105]
	v_mfma_f32_16x16x32_bf16 v[98:101], v[184:187], v[228:231], v[98:101]
	v_mfma_f32_16x16x32_bf16 v[86:89], v[172:175], v[236:239], v[86:89]
	v_mfma_f32_16x16x32_bf16 v[82:85], v[184:187], v[236:239], v[82:85]
	s_setprio 1
	s_barrier
	s_add_i32 s41, s41, s24
	v_lshl_add_u64 v[156:157], s[2:3], 0, v[0:1]
	s_mov_b32 m0, s41
	ds_read_b128 v[188:191], v183 offset:16384
	ds_read_b128 v[212:215], v183 offset:17408
	ds_read_b128 v[216:219], v183 offset:18432
	ds_read_b128 v[220:223], v183 offset:19456
	ds_read_b128 v[224:227], v183 offset:20480
	ds_read_b128 v[228:231], v183 offset:21504
	ds_read_b128 v[232:235], v183 offset:22528
	ds_read_b128 v[236:239], v183 offset:23552
	global_load_lds_dwordx4 v[156:157], off
	s_add_i32 m0, s41, 0x2000
	s_add_u32 s42, s2, 0x80000
	v_lshl_add_u64 v[192:193], s[2:3], 0, v[146:147]
	s_addc_u32 s43, s3, 0
	s_add_i32 s41, s44, s24
	global_load_lds_dwordx4 v[192:193], off
	v_lshl_add_u64 v[240:241], s[42:43], 0, v[0:1]
	s_mov_b32 m0, s41
	v_lshl_add_u64 v[242:243], s[4:5], 0, v[148:149]
	global_load_lds_dwordx4 v[240:241], off
	v_lshl_add_u64 v[240:241], s[42:43], 0, v[146:147]
	s_add_i32 m0, s41, 0x2000
	s_nop 0
	global_load_lds_dwordx4 v[240:241], off
	v_lshl_add_u64 v[240:241], s[4:5], 0, v[150:151]
	s_mov_b32 m0, s25
	s_nop 0
	global_load_lds_dwordx4 v[240:241], off
	s_mov_b32 m0, s26
	s_nop 0
	global_load_lds_dwordx4 v[242:243], off
	s_waitcnt vmcnt(8)
	s_waitcnt lgkmcnt(0)
	s_barrier
; #define PG8_STAGE(bufoff, gbase, voff) do { _Pragma("unroll") for (int _i = 0; _i < 2; ++_i) \
;         __builtin_amdgcn_global_load_lds((const unsigned*)((const char*)(gbase) + (voff)[_i]), (PG8_LAS unsigned*)(lds + (bufoff) + ldsw + _i * 8192), 16, 0, 0); } while (0)
; #define PG8_LDA(dst, b, h) do { _Pragma("unroll") for (int m = 0; m < 4; ++m) _Pragma("unroll") for (int k = 0; k < 2; ++k) dst[m][k] = *(const PG8_LAS bf16x8*)(lds + PG8_SA(b, h) + aoff + m * 2048 + k * 1024); } while (0)
; #define PG8_LDB(dst, b, h) do { _Pragma("unroll") for (int n = 0; n < 2; ++n) _Pragma("unroll") for (int k = 0; k < 2; ++k) dst[n][k] = *(const PG8_LAS bf16x8*)(lds + PG8_SB(b, h) + boff + n * 2048 + k * 1024); } while (0)
; #define PG8_MMA(ai, bj, At, Bt) do { __builtin_amdgcn_s_setprio(1); _Pragma("unroll") for (int m = 0; m < 4; ++m) _Pragma("unroll") for (int n = 0; n < 2; ++n) _Pragma("unroll") for (int k = 0; k < 2; ++k) \
;         acc[ai][bj][m][n] = __builtin_amdgcn_mfma_f32_16x16x32_bf16(Bt[n][k], At[m][k], acc[ai][bj][m][n], 0, 0, 0); __builtin_amdgcn_s_setprio(0); } while (0)
; #define PG8_WAIT_V(n) asm volatile("s_waitcnt vmcnt(" #n ")" ::: "memory")
; #define PG8_WAIT_L(n) asm volatile("s_waitcnt lgkmcnt(" #n ")" ::: "memory")
; #define PG8_BAR __builtin_amdgcn_s_barrier()
; #define PG8_SCHED __builtin_amdgcn_sched_barrier(0)
; template <class Epi, class Sched, bool ALIGN_EPI = false, bool SP2 = false>
; __device__ __forceinline__ void gemm_phase(PG8_LAS unsigned char* lds, const Gemm g, const Sched& S, const Epi& E, int wave_in) {
;     ...
;             PG8_WAIT_V(8); PG8_WAIT_L(0); PG8_BAR; PG8_MMA(1, 0, At, B0); PG8_MMA(1, 1, At, B1); PG8_BAR; PG8_SCHED;
;             PG8_LDB(B0, 1, 0); PG8_LDB(B1, 1, 1); PG8_SCHED; PG8_LDA(At, 1, 0); PG8_STAGE(PG8_SA(0, 1), a2 + hstepA, voffA);
;             PG8_WAIT_V(8); PG8_WAIT_L(0); PG8_BAR; PG8_MMA(0, 0, At, B0); PG8_MMA(0, 1, At, B1); PG8_BAR; PG8_SCHED;
	s_setprio 0
	s_waitcnt lgkmcnt(0)
	v_mfma_f32_16x16x32_bf16 v[78:81], v[26:29], v[188:191], v[78:81]
	v_mfma_f32_16x16x32_bf16 v[74:77], v[42:45], v[188:191], v[74:77]
	v_mfma_f32_16x16x32_bf16 v[62:65], v[26:29], v[216:219], v[62:65]
	v_mfma_f32_16x16x32_bf16 v[58:61], v[42:45], v[216:219], v[58:61]
	v_mfma_f32_16x16x32_bf16 v[38:41], v[26:29], v[224:227], v[38:41]
	v_mfma_f32_16x16x32_bf16 v[34:37], v[42:45], v[224:227], v[34:37]
	v_mfma_f32_16x16x32_bf16 v[14:17], v[26:29], v[232:235], v[14:17]
	v_mfma_f32_16x16x32_bf16 v[10:13], v[42:45], v[232:235], v[10:13]
	v_mfma_f32_16x16x32_bf16 v[78:81], v[30:33], v[212:215], v[78:81]
	v_mfma_f32_16x16x32_bf16 v[74:77], v[46:49], v[212:215], v[74:77]
	v_mfma_f32_16x16x32_bf16 v[62:65], v[30:33], v[220:223], v[62:65]
	v_mfma_f32_16x16x32_bf16 v[58:61], v[46:49], v[220:223], v[58:61]
	v_mfma_f32_16x16x32_bf16 v[38:41], v[30:33], v[228:231], v[38:41]
	v_mfma_f32_16x16x32_bf16 v[34:37], v[46:49], v[228:231], v[34:37]
	v_mfma_f32_16x16x32_bf16 v[14:17], v[30:33], v[236:239], v[14:17]
	v_mfma_f32_16x16x32_bf16 v[10:13], v[46:49], v[236:239], v[10:13]
	v_mfma_f32_16x16x32_bf16 v[22:25], v[168:171], v[224:227], v[22:25]
	v_mfma_f32_16x16x32_bf16 v[18:21], v[176:179], v[224:227], v[18:21]
	v_mfma_f32_16x16x32_bf16 v[6:9], v[168:171], v[232:235], v[6:9]
	v_mfma_f32_16x16x32_bf16 v[2:5], v[176:179], v[232:235], v[2:5]
	v_mfma_f32_16x16x32_bf16 v[26:29], v[168:171], v[188:191], v[70:73]
	v_mfma_f32_16x16x32_bf16 v[30:33], v[176:179], v[188:191], v[66:69]
	v_mfma_f32_16x16x32_bf16 v[42:45], v[168:171], v[216:219], v[54:57]
	v_mfma_f32_16x16x32_bf16 v[46:49], v[176:179], v[216:219], v[50:53]
	v_mfma_f32_16x16x32_bf16 v[22:25], v[172:175], v[228:231], v[22:25]
	v_mfma_f32_16x16x32_bf16 v[18:21], v[184:187], v[228:231], v[18:21]
	v_mfma_f32_16x16x32_bf16 v[6:9], v[172:175], v[236:239], v[6:9]
	v_mfma_f32_16x16x32_bf16 v[2:5], v[184:187], v[236:239], v[2:5]
	v_mfma_f32_16x16x32_bf16 v[26:29], v[172:175], v[212:215], v[26:29]
	v_mfma_f32_16x16x32_bf16 v[30:33], v[184:187], v[212:215], v[30:33]
	v_mfma_f32_16x16x32_bf16 v[42:45], v[172:175], v[220:223], v[42:45]
	v_mfma_f32_16x16x32_bf16 v[46:49], v[184:187], v[220:223], v[46:49]
	s_setprio 1
	s_barrier
	s_add_i32 s41, 0, 0x18000
	s_add_i32 s42, 0, 0x1c000
	v_add_u32_e32 v70, s41, v181
	v_add_u32_e32 v184, s42, v181
	ds_read_b128 v[50:53], v70
	ds_read_b128 v[54:57], v70 offset:1024
	ds_read_b128 v[66:69], v70 offset:2048
	ds_read_b128 v[70:73], v70 offset:3072
	ds_read_b128 v[168:171], v184
	ds_read_b128 v[172:175], v184 offset:1024
	ds_read_b128 v[176:179], v184 offset:2048
	ds_read_b128 v[184:187], v184 offset:3072
	s_add_u32 s4, s4, 0x80000
	s_addc_u32 s5, s5, 0
	s_mov_b32 m0, s27
	v_lshl_add_u64 v[244:245], s[4:5], 0, v[150:151]
	ds_read_b128 v[188:191], v183 offset:32768
	ds_read_b128 v[212:215], v183 offset:33792
	ds_read_b128 v[216:219], v183 offset:34816
	ds_read_b128 v[220:223], v183 offset:35840
	ds_read_b128 v[224:227], v183 offset:36864
	ds_read_b128 v[228:231], v183 offset:37888
	ds_read_b128 v[232:235], v183 offset:38912
	ds_read_b128 v[236:239], v183 offset:39936
	global_load_lds_dwordx4 v[244:245], off
	v_lshl_add_u64 v[244:245], s[4:5], 0, v[148:149]
	s_mov_b32 m0, s28
	s_nop 0
	global_load_lds_dwordx4 v[244:245], off
	s_waitcnt vmcnt(8)
	s_waitcnt lgkmcnt(0)
	s_barrier
	s_setprio 0
	s_waitcnt lgkmcnt(0)
	v_mfma_f32_16x16x32_bf16 v[142:145], v[50:53], v[188:191], v[142:145]
	v_mfma_f32_16x16x32_bf16 v[138:141], v[66:69], v[188:191], v[138:141]
	v_mfma_f32_16x16x32_bf16 v[126:129], v[50:53], v[216:219], v[126:129]
	v_mfma_f32_16x16x32_bf16 v[122:125], v[66:69], v[216:219], v[122:125]
	v_mfma_f32_16x16x32_bf16 v[110:113], v[50:53], v[224:227], v[110:113]
	v_mfma_f32_16x16x32_bf16 v[106:109], v[66:69], v[224:227], v[106:109]
	v_mfma_f32_16x16x32_bf16 v[94:97], v[50:53], v[232:235], v[94:97]
	v_mfma_f32_16x16x32_bf16 v[90:93], v[66:69], v[232:235], v[90:93]
	v_mfma_f32_16x16x32_bf16 v[142:145], v[54:57], v[212:215], v[142:145]
	v_mfma_f32_16x16x32_bf16 v[138:141], v[70:73], v[212:215], v[138:141]
	v_mfma_f32_16x16x32_bf16 v[126:129], v[54:57], v[220:223], v[126:129]
	v_mfma_f32_16x16x32_bf16 v[122:125], v[70:73], v[220:223], v[122:125]
	v_mfma_f32_16x16x32_bf16 v[110:113], v[54:57], v[228:231], v[110:113]
	v_mfma_f32_16x16x32_bf16 v[106:109], v[70:73], v[228:231], v[106:109]
	v_mfma_f32_16x16x32_bf16 v[94:97], v[54:57], v[236:239], v[94:97]
	v_mfma_f32_16x16x32_bf16 v[90:93], v[70:73], v[236:239], v[90:93]
	v_mfma_f32_16x16x32_bf16 v[134:137], v[168:171], v[188:191], v[134:137]
	v_mfma_f32_16x16x32_bf16 v[130:133], v[176:179], v[188:191], v[130:133]
	v_mfma_f32_16x16x32_bf16 v[118:121], v[168:171], v[216:219], v[118:121]
	v_mfma_f32_16x16x32_bf16 v[114:117], v[176:179], v[216:219], v[114:117]
	v_mfma_f32_16x16x32_bf16 v[102:105], v[168:171], v[224:227], v[102:105]
	v_mfma_f32_16x16x32_bf16 v[98:101], v[176:179], v[224:227], v[98:101]
	v_mfma_f32_16x16x32_bf16 v[86:89], v[168:171], v[232:235], v[86:89]
	v_mfma_f32_16x16x32_bf16 v[82:85], v[176:179], v[232:235], v[82:85]
	v_mfma_f32_16x16x32_bf16 v[134:137], v[172:175], v[212:215], v[134:137]
	v_mfma_f32_16x16x32_bf16 v[130:133], v[184:187], v[212:215], v[130:133]
	v_mfma_f32_16x16x32_bf16 v[118:121], v[172:175], v[220:223], v[118:121]
	v_mfma_f32_16x16x32_bf16 v[114:117], v[184:187], v[220:223], v[114:117]
	v_mfma_f32_16x16x32_bf16 v[102:105], v[172:175], v[228:231], v[102:105]
	v_mfma_f32_16x16x32_bf16 v[98:101], v[184:187], v[228:231], v[98:101]
	v_mfma_f32_16x16x32_bf16 v[86:89], v[172:175], v[236:239], v[86:89]
	v_mfma_f32_16x16x32_bf16 v[82:85], v[184:187], v[236:239], v[82:85]
	s_setprio 1
	s_barrier
; #define PG8_STAGE(bufoff, gbase, voff) do { _Pragma("unroll") for (int _i = 0; _i < 2; ++_i) \
;         __builtin_amdgcn_global_load_lds((const unsigned*)((const char*)(gbase) + (voff)[_i]), (PG8_LAS unsigned*)(lds + (bufoff) + ldsw + _i * 8192), 16, 0, 0); } while (0)
; #define PG8_LDA(dst, b, h) do { _Pragma("unroll") for (int m = 0; m < 4; ++m) _Pragma("unroll") for (int k = 0; k < 2; ++k) dst[m][k] = *(const PG8_LAS bf16x8*)(lds + PG8_SA(b, h) + aoff + m * 2048 + k * 1024); } while (0)
; #define PG8_MMA(ai, bj, At, Bt) do { __builtin_amdgcn_s_setprio(1); _Pragma("unroll") for (int m = 0; m < 4; ++m) _Pragma("unroll") for (int n = 0; n < 2; ++n) _Pragma("unroll") for (int k = 0; k < 2; ++k) \
;         acc[ai][bj][m][n] = __builtin_amdgcn_mfma_f32_16x16x32_bf16(Bt[n][k], At[m][k], acc[ai][bj][m][n], 0, 0, 0); __builtin_amdgcn_s_setprio(0); } while (0)
; #define PG8_WAIT_V(n) asm volatile("s_waitcnt vmcnt(" #n ")" ::: "memory")
; #define PG8_WAIT_L(n) asm volatile("s_waitcnt lgkmcnt(" #n ")" ::: "memory")
; #define PG8_BAR __builtin_amdgcn_s_barrier()
; #define PG8_SCHED __builtin_amdgcn_sched_barrier(0)
; template <class Epi, class Sched, bool ALIGN_EPI = false, bool SP2 = false>
; __device__ __forceinline__ void gemm_phase(PG8_LAS unsigned char* lds, const Gemm g, const Sched& S, const Epi& E, int wave_in) {
;     ...
;         for (int t = 0; t < nt; t += 2) {
;             const bool last = (t == nt - 2);
;             const char* a1 = cA + (size_t)(t + 1) * kstep;
;             const char* a2 = last ? nA : cA + (size_t)(t + 2) * kstep; const char* b2 = last ? nB : cB + (size_t)(t + 2) * kstep;
;     ...
;             PG8_LDA(At, 1, 1); PG8_STAGE(PG8_SB(1, 0), b3, voffB); PG8_STAGE(PG8_SB(1, 1), b3 + hstep, voffB); PG8_STAGE(PG8_SA(1, 0), a3, voffA);
;             PG8_WAIT_V(8); PG8_WAIT_L(0); PG8_BAR; PG8_MMA(1, 0, At, B0); PG8_MMA(1, 1, At, B1); PG8_BAR; PG8_SCHED;
	s_add_i32 s4, s41, s24
	v_lshl_add_u64 v[156:157], v[156:157], 0, s[84:85]
	s_mov_b32 m0, s4
	ds_read_b128 v[188:191], v183 offset:49152
	ds_read_b128 v[212:215], v183 offset:50176
	ds_read_b128 v[216:219], v183 offset:51200
	ds_read_b128 v[220:223], v183 offset:52224
	ds_read_b128 v[224:227], v183 offset:53248
	ds_read_b128 v[228:231], v183 offset:54272
	ds_read_b128 v[232:235], v183 offset:55296
	ds_read_b128 v[236:239], v183 offset:56320
	global_load_lds_dwordx4 v[156:157], off
	s_add_i32 m0, s4, 0x2000
	s_add_u32 s2, s2, 0x80080
	v_lshl_add_u64 v[156:157], v[192:193], 0, s[84:85]
	s_addc_u32 s3, s3, 0
	s_add_i32 s4, s42, s24
	global_load_lds_dwordx4 v[156:157], off
	v_lshl_add_u64 v[156:157], s[2:3], 0, v[0:1]
	s_mov_b32 m0, s4
	s_nop 0
	global_load_lds_dwordx4 v[156:157], off
	v_lshl_add_u64 v[156:157], s[2:3], 0, v[146:147]
	s_add_i32 m0, s4, 0x2000
	s_nop 0
	global_load_lds_dwordx4 v[156:157], off
	v_lshl_add_u64 v[156:157], v[240:241], 0, s[84:85]
	s_mov_b32 m0, s29
	s_nop 0
	global_load_lds_dwordx4 v[156:157], off
	v_lshl_add_u64 v[156:157], v[242:243], 0, s[84:85]
	s_mov_b32 m0, s30
	s_nop 0
	global_load_lds_dwordx4 v[156:157], off
	s_waitcnt vmcnt(8)
	s_waitcnt lgkmcnt(0)
	s_barrier
	s_setprio 0
	s_waitcnt lgkmcnt(0)
	v_mfma_f32_16x16x32_bf16 v[78:81], v[50:53], v[188:191], v[78:81]
	v_mfma_f32_16x16x32_bf16 v[74:77], v[66:69], v[188:191], v[74:77]
	v_mfma_f32_16x16x32_bf16 v[62:65], v[50:53], v[216:219], v[62:65]
	v_mfma_f32_16x16x32_bf16 v[58:61], v[66:69], v[216:219], v[58:61]
	v_mfma_f32_16x16x32_bf16 v[38:41], v[50:53], v[224:227], v[38:41]
	v_mfma_f32_16x16x32_bf16 v[34:37], v[66:69], v[224:227], v[34:37]
	v_mfma_f32_16x16x32_bf16 v[14:17], v[50:53], v[232:235], v[14:17]
	v_mfma_f32_16x16x32_bf16 v[10:13], v[66:69], v[232:235], v[10:13]
	v_mfma_f32_16x16x32_bf16 v[78:81], v[54:57], v[212:215], v[78:81]
	v_mfma_f32_16x16x32_bf16 v[74:77], v[70:73], v[212:215], v[74:77]
	v_mfma_f32_16x16x32_bf16 v[62:65], v[54:57], v[220:223], v[62:65]
	v_mfma_f32_16x16x32_bf16 v[58:61], v[70:73], v[220:223], v[58:61]
	v_mfma_f32_16x16x32_bf16 v[38:41], v[54:57], v[228:231], v[38:41]
	v_mfma_f32_16x16x32_bf16 v[34:37], v[70:73], v[228:231], v[34:37]
	v_mfma_f32_16x16x32_bf16 v[14:17], v[54:57], v[236:239], v[14:17]
	v_mfma_f32_16x16x32_bf16 v[10:13], v[70:73], v[236:239], v[10:13]
	v_mfma_f32_16x16x32_bf16 v[26:29], v[168:171], v[188:191], v[26:29]
	v_mfma_f32_16x16x32_bf16 v[70:73], v[172:175], v[212:215], v[26:29]
	v_mfma_f32_16x16x32_bf16 v[26:29], v[176:179], v[188:191], v[30:33]
	v_mfma_f32_16x16x32_bf16 v[66:69], v[184:187], v[212:215], v[26:29]
	v_mfma_f32_16x16x32_bf16 v[26:29], v[168:171], v[216:219], v[42:45]
	v_mfma_f32_16x16x32_bf16 v[54:57], v[172:175], v[220:223], v[26:29]
	v_mfma_f32_16x16x32_bf16 v[26:29], v[176:179], v[216:219], v[46:49]
	v_mfma_f32_16x16x32_bf16 v[22:25], v[168:171], v[224:227], v[22:25]
	v_mfma_f32_16x16x32_bf16 v[18:21], v[176:179], v[224:227], v[18:21]
	v_mfma_f32_16x16x32_bf16 v[6:9], v[168:171], v[232:235], v[6:9]
	v_mfma_f32_16x16x32_bf16 v[2:5], v[176:179], v[232:235], v[2:5]
	v_mfma_f32_16x16x32_bf16 v[50:53], v[184:187], v[220:223], v[26:29]
	v_mfma_f32_16x16x32_bf16 v[22:25], v[172:175], v[228:231], v[22:25]
	v_mfma_f32_16x16x32_bf16 v[18:21], v[184:187], v[228:231], v[18:21]
	v_mfma_f32_16x16x32_bf16 v[6:9], v[172:175], v[236:239], v[6:9]
	v_mfma_f32_16x16x32_bf16 v[2:5], v[184:187], v[236:239], v[2:5]
	s_setprio 1
	s_barrier
	s_add_i32 s40, s40, 2
	s_add_u32 s0, s0, 0x100
	s_addc_u32 s1, s1, 0
	s_add_u32 s38, s38, 0x100
	s_addc_u32 s39, s39, 0
	s_cmp_gt_u32 s40, 29
	s_cbranch_scc0 .LBB0_277
	s_and_b64 vcc, exec, s[14:15]
	s_cbranch_vccz .LBB0_280
	s_barrier

; #define PG8_STAGE(bufoff, gbase, voff) do { _Pragma("unroll") for (int _i = 0; _i < 2; ++_i) \
;         __builtin_amdgcn_global_load_lds((const unsigned*)((const char*)(gbase) + (voff)[_i]), (PG8_LAS unsigned*)(lds + (bufoff) + ldsw + _i * 8192), 16, 0, 0); } while (0)
; #define PG8_LDA(dst, b, h) do { _Pragma("unroll") for (int m = 0; m < 4; ++m) _Pragma("unroll") for (int k = 0; k < 2; ++k) dst[m][k] = *(const PG8_LAS bf16x8*)(lds + PG8_SA(b, h) + aoff + m * 2048 + k * 1024); } while (0)
; #define PG8_LDB(dst, b, h) do { _Pragma("unroll") for (int n = 0; n < 2; ++n) _Pragma("unroll") for (int k = 0; k < 2; ++k) dst[n][k] = *(const PG8_LAS bf16x8*)(lds + PG8_SB(b, h) + boff + n * 2048 + k * 1024); } while (0)
; #define PG8_WAIT_V(n) asm volatile("s_waitcnt vmcnt(" #n ")" ::: "memory")
; #define PG8_WAIT_L(n) asm volatile("s_waitcnt lgkmcnt(" #n ")" ::: "memory")
; #define PG8_BAR __builtin_amdgcn_s_barrier()
; #define PG8_SCHED __builtin_amdgcn_sched_barrier(0)
; template <class Epi, class Sched, bool ALIGN_EPI = false, bool SP2 = false>
; __device__ __forceinline__ void gemm_phase(PG8_LAS unsigned char* lds, const Gemm g, const Sched& S, const Epi& E, int wave_in) {
;     ...
;         const char* nA = has_next ? (const char*)g.A + (size_t)nxt.pm * tstepA : cA; const char* nB = has_next ? (const char*)g.Bt + (size_t)nxt.pn * tstep : cB;
;         for (int t = 0; t < nt; t += 2) {
;             const bool last = (t == nt - 2);
;             const char* a1 = cA + (size_t)(t + 1) * kstep;
;             const char* a2 = last ? nA : cA + (size_t)(t + 2) * kstep; const char* b2 = last ? nB : cB + (size_t)(t + 2) * kstep;
;             const char* a3 = a2 + kstep; const char* b3 = b2 + kstep;
;             if (last && has_next) S.a_ready(nxt);
;             if constexpr (SP2) {
;             PG8_LDB(B0, 0, 0); PG8_LDB(B1, 0, 1); PG8_SCHED; PG8_LDA(At, 0, 0); PG8_STAGE(PG8_SA(1, 1), a1 + hstepA, voffA);
;             PG8_WAIT_V(8); PG8_WAIT_L(0); PG8_BAR; PG8_MMA(0, 0, At, B0); PG8_MMA(0, 1, At, B1); PG8_BAR; PG8_SCHED;
;             PG8_LDA(At, 0, 1); PG8_STAGE(PG8_SB(0, 0), b2, voffB); PG8_STAGE(PG8_SB(0, 1), b2 + hstep, voffB); PG8_STAGE(PG8_SA(0, 0), a2, voffA);
;             PG8_WAIT_V(8); PG8_WAIT_L(0); PG8_BAR; PG8_MMA(1, 0, At, B0); PG8_MMA(1, 1, At, B1); PG8_BAR; PG8_SCHED;
.Lmg_nohook:
	s_add_i32 s43, s6, 2
	s_add_u32 s44, s4, 0x80
	s_addc_u32 s7, s5, 0
	s_add_i32 s46, 0, 0x10000
	s_cmp_eq_u32 s37, s6
	s_cselect_b32 s7, s21, s7
	s_cselect_b32 s6, s20, s44
	s_cselect_b32 s45, s23, s25
	s_cselect_b32 s44, s22, s24
	s_add_i32 s47, 0, 0x14000
	v_add_u32_e32 v168, s46, v149
	v_add_u32_e32 v184, s47, v149
	ds_read_b128 v[140:143], v168
	ds_read_b128 v[144:147], v168 offset:1024
	ds_read_b128 v[154:157], v168 offset:2048
	ds_read_b128 v[168:171], v168 offset:3072
	ds_read_b128 v[172:175], v184
	ds_read_b128 v[176:179], v184 offset:1024
	ds_read_b128 v[180:183], v184 offset:2048
	ds_read_b128 v[184:187], v184 offset:3072
	v_lshl_add_u64 v[192:193], s[4:5], 0, v[136:137]
	s_add_i32 m0, s28, 0xc000
	ds_read_b128 v[188:191], v153
	ds_read_b128 v[212:215], v153 offset:1024
	ds_read_b128 v[216:219], v153 offset:2048
	ds_read_b128 v[220:223], v153 offset:3072
	ds_read_b128 v[224:227], v153 offset:4096
	ds_read_b128 v[228:231], v153 offset:5120
	ds_read_b128 v[232:235], v153 offset:6144
	ds_read_b128 v[236:239], v153 offset:7168
	global_load_lds_dwordx4 v[192:193], off
	v_lshl_add_u64 v[192:193], s[4:5], 0, v[138:139]
	s_add_i32 m0, s28, 0xe000
	s_nop 0
	global_load_lds_dwordx4 v[192:193], off
	s_waitcnt vmcnt(8)
	s_waitcnt lgkmcnt(0)
	s_barrier
	s_setprio 0
	s_waitcnt lgkmcnt(0)
	v_mfma_f32_16x16x32_bf16 v[126:129], v[140:143], v[188:191], v[126:129]
	v_mfma_f32_16x16x32_bf16 v[122:125], v[154:157], v[188:191], v[122:125]
	v_mfma_f32_16x16x32_bf16 v[110:113], v[140:143], v[216:219], v[110:113]
	v_mfma_f32_16x16x32_bf16 v[106:109], v[154:157], v[216:219], v[106:109]
	v_mfma_f32_16x16x32_bf16 v[94:97], v[140:143], v[224:227], v[94:97]
	v_mfma_f32_16x16x32_bf16 v[90:93], v[154:157], v[224:227], v[90:93]
	v_mfma_f32_16x16x32_bf16 v[78:81], v[140:143], v[232:235], v[78:81]
	v_mfma_f32_16x16x32_bf16 v[74:77], v[154:157], v[232:235], v[74:77]
	v_mfma_f32_16x16x32_bf16 v[126:129], v[144:147], v[212:215], v[126:129]
	v_mfma_f32_16x16x32_bf16 v[122:125], v[168:171], v[212:215], v[122:125]
	v_mfma_f32_16x16x32_bf16 v[110:113], v[144:147], v[220:223], v[110:113]
	v_mfma_f32_16x16x32_bf16 v[106:109], v[168:171], v[220:223], v[106:109]
	v_mfma_f32_16x16x32_bf16 v[94:97], v[144:147], v[228:231], v[94:97]
	v_mfma_f32_16x16x32_bf16 v[90:93], v[168:171], v[228:231], v[90:93]
	v_mfma_f32_16x16x32_bf16 v[78:81], v[144:147], v[236:239], v[78:81]
	v_mfma_f32_16x16x32_bf16 v[74:77], v[168:171], v[236:239], v[74:77]
	v_mfma_f32_16x16x32_bf16 v[118:121], v[172:175], v[188:191], v[118:121]
	v_mfma_f32_16x16x32_bf16 v[114:117], v[180:183], v[188:191], v[114:117]
	v_mfma_f32_16x16x32_bf16 v[102:105], v[172:175], v[216:219], v[102:105]
	v_mfma_f32_16x16x32_bf16 v[98:101], v[180:183], v[216:219], v[98:101]
	v_mfma_f32_16x16x32_bf16 v[86:89], v[172:175], v[224:227], v[86:89]
	v_mfma_f32_16x16x32_bf16 v[82:85], v[180:183], v[224:227], v[82:85]
	v_mfma_f32_16x16x32_bf16 v[70:73], v[172:175], v[232:235], v[70:73]
	v_mfma_f32_16x16x32_bf16 v[66:69], v[180:183], v[232:235], v[66:69]
	v_mfma_f32_16x16x32_bf16 v[118:121], v[176:179], v[212:215], v[118:121]
	v_mfma_f32_16x16x32_bf16 v[114:117], v[184:187], v[212:215], v[114:117]
	v_mfma_f32_16x16x32_bf16 v[102:105], v[176:179], v[220:223], v[102:105]
	v_mfma_f32_16x16x32_bf16 v[98:101], v[184:187], v[220:223], v[98:101]
	v_mfma_f32_16x16x32_bf16 v[86:89], v[176:179], v[228:231], v[86:89]
	v_mfma_f32_16x16x32_bf16 v[82:85], v[184:187], v[228:231], v[82:85]
	v_mfma_f32_16x16x32_bf16 v[70:73], v[176:179], v[236:239], v[70:73]
	v_mfma_f32_16x16x32_bf16 v[66:69], v[184:187], v[236:239], v[66:69]
	s_setprio 1
	s_barrier
	s_add_i32 s46, s46, s27
	v_lshl_add_u64 v[192:193], s[44:45], 0, v[0:1]
	s_mov_b32 m0, s46
	ds_read_b128 v[188:191], v153 offset:16384
	ds_read_b128 v[212:215], v153 offset:17408
	ds_read_b128 v[216:219], v153 offset:18432
	ds_read_b128 v[220:223], v153 offset:19456
	ds_read_b128 v[224:227], v153 offset:20480
	ds_read_b128 v[228:231], v153 offset:21504
	ds_read_b128 v[232:235], v153 offset:22528
	ds_read_b128 v[236:239], v153 offset:23552
	global_load_lds_dwordx4 v[192:193], off
	s_add_i32 m0, s46, 0x2000
	v_lshl_add_u64 v[200:201], s[44:45], 0, v[130:131]
	s_add_u32 s44, s44, s78
	s_addc_u32 s45, s45, 0
	s_add_i32 s46, s47, s27
	global_load_lds_dwordx4 v[200:201], off
	v_lshl_add_u64 v[240:241], s[44:45], 0, v[0:1]
	s_mov_b32 m0, s46
	v_lshl_add_u64 v[242:243], s[44:45], 0, v[130:131]
	global_load_lds_dwordx4 v[240:241], off
	s_add_i32 m0, s46, 0x2000
	v_lshl_add_u64 v[244:245], s[6:7], 0, v[134:135]
	global_load_lds_dwordx4 v[242:243], off
	s_mov_b32 m0, s28
	v_lshl_add_u64 v[246:247], s[6:7], 0, v[132:133]
	global_load_lds_dwordx4 v[244:245], off
	s_mov_b32 m0, s29
	s_nop 0
	global_load_lds_dwordx4 v[246:247], off
	s_waitcnt vmcnt(8)
	s_waitcnt lgkmcnt(0)
	s_barrier
; #define PG8_STAGE(bufoff, gbase, voff) do { _Pragma("unroll") for (int _i = 0; _i < 2; ++_i) \
;         __builtin_amdgcn_global_load_lds((const unsigned*)((const char*)(gbase) + (voff)[_i]), (PG8_LAS unsigned*)(lds + (bufoff) + ldsw + _i * 8192), 16, 0, 0); } while (0)
; #define PG8_LDA(dst, b, h) do { _Pragma("unroll") for (int m = 0; m < 4; ++m) _Pragma("unroll") for (int k = 0; k < 2; ++k) dst[m][k] = *(const PG8_LAS bf16x8*)(lds + PG8_SA(b, h) + aoff + m * 2048 + k * 1024); } while (0)
; #define PG8_LDB(dst, b, h) do { _Pragma("unroll") for (int n = 0; n < 2; ++n) _Pragma("unroll") for (int k = 0; k < 2; ++k) dst[n][k] = *(const PG8_LAS bf16x8*)(lds + PG8_SB(b, h) + boff + n * 2048 + k * 1024); } while (0)
; #define PG8_MMA(ai, bj, At, Bt) do { __builtin_amdgcn_s_setprio(1); _Pragma("unroll") for (int m = 0; m < 4; ++m) _Pragma("unroll") for (int n = 0; n < 2; ++n) _Pragma("unroll") for (int k = 0; k < 2; ++k) \
;         acc[ai][bj][m][n] = __builtin_amdgcn_mfma_f32_16x16x32_bf16(Bt[n][k], At[m][k], acc[ai][bj][m][n], 0, 0, 0); __builtin_amdgcn_s_setprio(0); } while (0)
; #define PG8_WAIT_V(n) asm volatile("s_waitcnt vmcnt(" #n ")" ::: "memory")
; #define PG8_WAIT_L(n) asm volatile("s_waitcnt lgkmcnt(" #n ")" ::: "memory")
; #define PG8_BAR __builtin_amdgcn_s_barrier()
; #define PG8_SCHED __builtin_amdgcn_sched_barrier(0)
; template <class Epi, class Sched, bool ALIGN_EPI = false, bool SP2 = false>
; __device__ __forceinline__ void gemm_phase(PG8_LAS unsigned char* lds, const Gemm g, const Sched& S, const Epi& E, int wave_in) {
;     ...
;             PG8_WAIT_V(8); PG8_WAIT_L(0); PG8_BAR; PG8_MMA(1, 0, At, B0); PG8_MMA(1, 1, At, B1); PG8_BAR; PG8_SCHED;
;             PG8_LDB(B0, 1, 0); PG8_LDB(B1, 1, 1); PG8_SCHED; PG8_LDA(At, 1, 0); PG8_STAGE(PG8_SA(0, 1), a2 + hstepA, voffA);
;             PG8_WAIT_V(8); PG8_WAIT_L(0); PG8_BAR; PG8_MMA(0, 0, At, B0); PG8_MMA(0, 1, At, B1); PG8_BAR; PG8_SCHED;
	s_setprio 0
	s_waitcnt lgkmcnt(0)
	v_mfma_f32_16x16x32_bf16 v[62:65], v[140:143], v[188:191], v[62:65]
	v_mfma_f32_16x16x32_bf16 v[58:61], v[154:157], v[188:191], v[58:61]
	v_mfma_f32_16x16x32_bf16 v[46:49], v[140:143], v[216:219], v[46:49]
	v_mfma_f32_16x16x32_bf16 v[42:45], v[154:157], v[216:219], v[42:45]
	v_mfma_f32_16x16x32_bf16 v[30:33], v[140:143], v[224:227], v[30:33]
	v_mfma_f32_16x16x32_bf16 v[26:29], v[154:157], v[224:227], v[26:29]
	v_mfma_f32_16x16x32_bf16 v[14:17], v[140:143], v[232:235], v[14:17]
	v_mfma_f32_16x16x32_bf16 v[10:13], v[154:157], v[232:235], v[10:13]
	v_mfma_f32_16x16x32_bf16 v[62:65], v[144:147], v[212:215], v[62:65]
	v_mfma_f32_16x16x32_bf16 v[58:61], v[168:171], v[212:215], v[58:61]
	v_mfma_f32_16x16x32_bf16 v[46:49], v[144:147], v[220:223], v[46:49]
	v_mfma_f32_16x16x32_bf16 v[42:45], v[168:171], v[220:223], v[42:45]
	v_mfma_f32_16x16x32_bf16 v[30:33], v[144:147], v[228:231], v[30:33]
	v_mfma_f32_16x16x32_bf16 v[26:29], v[168:171], v[228:231], v[26:29]
	v_mfma_f32_16x16x32_bf16 v[14:17], v[144:147], v[236:239], v[14:17]
	v_mfma_f32_16x16x32_bf16 v[10:13], v[168:171], v[236:239], v[10:13]
	v_mfma_f32_16x16x32_bf16 v[54:57], v[172:175], v[188:191], v[54:57]
	v_mfma_f32_16x16x32_bf16 v[50:53], v[180:183], v[188:191], v[50:53]
	v_mfma_f32_16x16x32_bf16 v[38:41], v[172:175], v[216:219], v[38:41]
	v_mfma_f32_16x16x32_bf16 v[34:37], v[180:183], v[216:219], v[34:37]
	v_mfma_f32_16x16x32_bf16 v[22:25], v[172:175], v[224:227], v[22:25]
	v_mfma_f32_16x16x32_bf16 v[18:21], v[180:183], v[224:227], v[18:21]
	v_mfma_f32_16x16x32_bf16 v[6:9], v[172:175], v[232:235], v[6:9]
	v_mfma_f32_16x16x32_bf16 v[2:5], v[180:183], v[232:235], v[2:5]
	v_mfma_f32_16x16x32_bf16 v[54:57], v[176:179], v[212:215], v[54:57]
	v_mfma_f32_16x16x32_bf16 v[50:53], v[184:187], v[212:215], v[50:53]
	v_mfma_f32_16x16x32_bf16 v[38:41], v[176:179], v[220:223], v[38:41]
	v_mfma_f32_16x16x32_bf16 v[34:37], v[184:187], v[220:223], v[34:37]
	v_mfma_f32_16x16x32_bf16 v[22:25], v[176:179], v[228:231], v[22:25]
	v_mfma_f32_16x16x32_bf16 v[18:21], v[184:187], v[228:231], v[18:21]
	v_mfma_f32_16x16x32_bf16 v[6:9], v[176:179], v[236:239], v[6:9]
	v_mfma_f32_16x16x32_bf16 v[2:5], v[184:187], v[236:239], v[2:5]
	s_setprio 1
	s_barrier
	s_add_i32 s44, 0, 0x18000
	s_add_i32 s45, 0, 0x1c000
	v_add_u32_e32 v168, s44, v149
	v_add_u32_e32 v184, s45, v149
	ds_read_b128 v[140:143], v168
	ds_read_b128 v[144:147], v168 offset:1024
	ds_read_b128 v[154:157], v168 offset:2048
	ds_read_b128 v[168:171], v168 offset:3072
	ds_read_b128 v[172:175], v184
	ds_read_b128 v[176:179], v184 offset:1024
	ds_read_b128 v[180:183], v184 offset:2048
	ds_read_b128 v[184:187], v184 offset:3072
	s_add_u32 s6, s6, s78
	s_addc_u32 s7, s7, 0
	s_mov_b32 m0, s30
	v_lshl_add_u64 v[248:249], s[6:7], 0, v[134:135]
	ds_read_b128 v[188:191], v153 offset:32768
	ds_read_b128 v[212:215], v153 offset:33792
	ds_read_b128 v[216:219], v153 offset:34816
	ds_read_b128 v[220:223], v153 offset:35840
	ds_read_b128 v[224:227], v153 offset:36864
	ds_read_b128 v[228:231], v153 offset:37888
	ds_read_b128 v[232:235], v153 offset:38912
	ds_read_b128 v[236:239], v153 offset:39936
	global_load_lds_dwordx4 v[248:249], off
	v_lshl_add_u64 v[248:249], s[6:7], 0, v[132:133]
	s_mov_b32 m0, s31
	s_nop 0
	global_load_lds_dwordx4 v[248:249], off
	s_waitcnt vmcnt(8)
	s_waitcnt lgkmcnt(0)
	s_barrier
	s_setprio 0
	s_waitcnt lgkmcnt(0)
	v_mfma_f32_16x16x32_bf16 v[126:129], v[140:143], v[188:191], v[126:129]
	v_mfma_f32_16x16x32_bf16 v[122:125], v[154:157], v[188:191], v[122:125]
	v_mfma_f32_16x16x32_bf16 v[110:113], v[140:143], v[216:219], v[110:113]
	v_mfma_f32_16x16x32_bf16 v[106:109], v[154:157], v[216:219], v[106:109]
	v_mfma_f32_16x16x32_bf16 v[94:97], v[140:143], v[224:227], v[94:97]
	v_mfma_f32_16x16x32_bf16 v[90:93], v[154:157], v[224:227], v[90:93]
	v_mfma_f32_16x16x32_bf16 v[78:81], v[140:143], v[232:235], v[78:81]
	v_mfma_f32_16x16x32_bf16 v[74:77], v[154:157], v[232:235], v[74:77]
	v_mfma_f32_16x16x32_bf16 v[126:129], v[144:147], v[212:215], v[126:129]
	v_mfma_f32_16x16x32_bf16 v[122:125], v[168:171], v[212:215], v[122:125]
	v_mfma_f32_16x16x32_bf16 v[110:113], v[144:147], v[220:223], v[110:113]
	v_mfma_f32_16x16x32_bf16 v[106:109], v[168:171], v[220:223], v[106:109]
	v_mfma_f32_16x16x32_bf16 v[94:97], v[144:147], v[228:231], v[94:97]
	v_mfma_f32_16x16x32_bf16 v[90:93], v[168:171], v[228:231], v[90:93]
	v_mfma_f32_16x16x32_bf16 v[78:81], v[144:147], v[236:239], v[78:81]
	v_mfma_f32_16x16x32_bf16 v[74:77], v[168:171], v[236:239], v[74:77]
	v_mfma_f32_16x16x32_bf16 v[118:121], v[172:175], v[188:191], v[118:121]
	v_mfma_f32_16x16x32_bf16 v[114:117], v[180:183], v[188:191], v[114:117]
	v_mfma_f32_16x16x32_bf16 v[102:105], v[172:175], v[216:219], v[102:105]
	v_mfma_f32_16x16x32_bf16 v[98:101], v[180:183], v[216:219], v[98:101]
	v_mfma_f32_16x16x32_bf16 v[86:89], v[172:175], v[224:227], v[86:89]
	v_mfma_f32_16x16x32_bf16 v[82:85], v[180:183], v[224:227], v[82:85]
	v_mfma_f32_16x16x32_bf16 v[70:73], v[172:175], v[232:235], v[70:73]
	v_mfma_f32_16x16x32_bf16 v[66:69], v[180:183], v[232:235], v[66:69]
	v_mfma_f32_16x16x32_bf16 v[118:121], v[176:179], v[212:215], v[118:121]
	v_mfma_f32_16x16x32_bf16 v[114:117], v[184:187], v[212:215], v[114:117]
	v_mfma_f32_16x16x32_bf16 v[102:105], v[176:179], v[220:223], v[102:105]
	v_mfma_f32_16x16x32_bf16 v[98:101], v[184:187], v[220:223], v[98:101]
	v_mfma_f32_16x16x32_bf16 v[86:89], v[176:179], v[228:231], v[86:89]
	v_mfma_f32_16x16x32_bf16 v[82:85], v[184:187], v[228:231], v[82:85]
	v_mfma_f32_16x16x32_bf16 v[70:73], v[176:179], v[236:239], v[70:73]
	v_mfma_f32_16x16x32_bf16 v[66:69], v[184:187], v[236:239], v[66:69]
	s_setprio 1
	s_barrier
; #define PG8_STAGE(bufoff, gbase, voff) do { _Pragma("unroll") for (int _i = 0; _i < 2; ++_i) \
;         __builtin_amdgcn_global_load_lds((const unsigned*)((const char*)(gbase) + (voff)[_i]), (PG8_LAS unsigned*)(lds + (bufoff) + ldsw + _i * 8192), 16, 0, 0); } while (0)
; #define PG8_LDA(dst, b, h) do { _Pragma("unroll") for (int m = 0; m < 4; ++m) _Pragma("unroll") for (int k = 0; k < 2; ++k) dst[m][k] = *(const PG8_LAS bf16x8*)(lds + PG8_SA(b, h) + aoff + m * 2048 + k * 1024); } while (0)
; #define PG8_MMA(ai, bj, At, Bt) do { __builtin_amdgcn_s_setprio(1); _Pragma("unroll") for (int m = 0; m < 4; ++m) _Pragma("unroll") for (int n = 0; n < 2; ++n) _Pragma("unroll") for (int k = 0; k < 2; ++k) \
;         acc[ai][bj][m][n] = __builtin_amdgcn_mfma_f32_16x16x32_bf16(Bt[n][k], At[m][k], acc[ai][bj][m][n], 0, 0, 0); __builtin_amdgcn_s_setprio(0); } while (0)
; #define PG8_WAIT_V(n) asm volatile("s_waitcnt vmcnt(" #n ")" ::: "memory")
; #define PG8_WAIT_L(n) asm volatile("s_waitcnt lgkmcnt(" #n ")" ::: "memory")
; #define PG8_BAR __builtin_amdgcn_s_barrier()
; #define PG8_SCHED __builtin_amdgcn_sched_barrier(0)
; template <class Epi, class Sched, bool ALIGN_EPI = false, bool SP2 = false>
; __device__ __forceinline__ void gemm_phase(PG8_LAS unsigned char* lds, const Gemm g, const Sched& S, const Epi& E, int wave_in) {
;     ...
;         for (int t = 0; t < nt; t += 2) {
;     ...
;             PG8_LDA(At, 1, 1); PG8_STAGE(PG8_SB(1, 0), b3, voffB); PG8_STAGE(PG8_SB(1, 1), b3 + hstep, voffB); PG8_STAGE(PG8_SA(1, 0), a3, voffA);
;             PG8_WAIT_V(8); PG8_WAIT_L(0); PG8_BAR; PG8_MMA(1, 0, At, B0); PG8_MMA(1, 1, At, B1); PG8_BAR; PG8_SCHED;
	s_add_i32 s6, s44, s27
	v_lshl_add_u64 v[192:193], v[192:193], 0, s[84:85]
	s_mov_b32 m0, s6
	ds_read_b128 v[188:191], v153 offset:49152
	ds_read_b128 v[212:215], v153 offset:50176
	ds_read_b128 v[216:219], v153 offset:51200
	ds_read_b128 v[220:223], v153 offset:52224
	ds_read_b128 v[224:227], v153 offset:53248
	ds_read_b128 v[228:231], v153 offset:54272
	ds_read_b128 v[232:235], v153 offset:55296
	ds_read_b128 v[236:239], v153 offset:56320
	global_load_lds_dwordx4 v[192:193], off
	v_lshl_add_u64 v[192:193], v[200:201], 0, s[84:85]
	s_add_i32 m0, s6, 0x2000
	s_add_i32 s6, s45, s27
	global_load_lds_dwordx4 v[192:193], off
	v_lshl_add_u64 v[192:193], v[240:241], 0, s[84:85]
	s_mov_b32 m0, s6
	s_nop 0
	global_load_lds_dwordx4 v[192:193], off
	v_lshl_add_u64 v[192:193], v[242:243], 0, s[84:85]
	s_add_i32 m0, s6, 0x2000
	s_nop 0
	global_load_lds_dwordx4 v[192:193], off
	v_lshl_add_u64 v[192:193], v[244:245], 0, s[84:85]
	s_mov_b32 m0, s34
	s_nop 0
	global_load_lds_dwordx4 v[192:193], off
	v_lshl_add_u64 v[192:193], v[246:247], 0, s[84:85]
	s_mov_b32 m0, s35
	s_nop 0
	global_load_lds_dwordx4 v[192:193], off
	s_waitcnt vmcnt(8)
	s_waitcnt lgkmcnt(0)
	s_barrier
	s_setprio 0
	s_waitcnt lgkmcnt(0)
	v_mfma_f32_16x16x32_bf16 v[62:65], v[140:143], v[188:191], v[62:65]
	v_mfma_f32_16x16x32_bf16 v[58:61], v[154:157], v[188:191], v[58:61]
	v_mfma_f32_16x16x32_bf16 v[46:49], v[140:143], v[216:219], v[46:49]
	v_mfma_f32_16x16x32_bf16 v[42:45], v[154:157], v[216:219], v[42:45]
	v_mfma_f32_16x16x32_bf16 v[30:33], v[140:143], v[224:227], v[30:33]
	v_mfma_f32_16x16x32_bf16 v[26:29], v[154:157], v[224:227], v[26:29]
	v_mfma_f32_16x16x32_bf16 v[14:17], v[140:143], v[232:235], v[14:17]
	v_mfma_f32_16x16x32_bf16 v[10:13], v[154:157], v[232:235], v[10:13]
	v_mfma_f32_16x16x32_bf16 v[62:65], v[144:147], v[212:215], v[62:65]
	v_mfma_f32_16x16x32_bf16 v[58:61], v[168:171], v[212:215], v[58:61]
	v_mfma_f32_16x16x32_bf16 v[46:49], v[144:147], v[220:223], v[46:49]
	v_mfma_f32_16x16x32_bf16 v[42:45], v[168:171], v[220:223], v[42:45]
	v_mfma_f32_16x16x32_bf16 v[30:33], v[144:147], v[228:231], v[30:33]
	v_mfma_f32_16x16x32_bf16 v[26:29], v[168:171], v[228:231], v[26:29]
	v_mfma_f32_16x16x32_bf16 v[14:17], v[144:147], v[236:239], v[14:17]
	v_mfma_f32_16x16x32_bf16 v[10:13], v[168:171], v[236:239], v[10:13]
	v_mfma_f32_16x16x32_bf16 v[54:57], v[172:175], v[188:191], v[54:57]
	v_mfma_f32_16x16x32_bf16 v[50:53], v[180:183], v[188:191], v[50:53]
	v_mfma_f32_16x16x32_bf16 v[38:41], v[172:175], v[216:219], v[38:41]
	v_mfma_f32_16x16x32_bf16 v[34:37], v[180:183], v[216:219], v[34:37]
	v_mfma_f32_16x16x32_bf16 v[22:25], v[172:175], v[224:227], v[22:25]
	v_mfma_f32_16x16x32_bf16 v[18:21], v[180:183], v[224:227], v[18:21]
	v_mfma_f32_16x16x32_bf16 v[6:9], v[172:175], v[232:235], v[6:9]
	v_mfma_f32_16x16x32_bf16 v[2:5], v[180:183], v[232:235], v[2:5]
	v_mfma_f32_16x16x32_bf16 v[54:57], v[176:179], v[212:215], v[54:57]
	v_mfma_f32_16x16x32_bf16 v[50:53], v[184:187], v[212:215], v[50:53]
	v_mfma_f32_16x16x32_bf16 v[38:41], v[176:179], v[220:223], v[38:41]
	v_mfma_f32_16x16x32_bf16 v[34:37], v[184:187], v[220:223], v[34:37]
	v_mfma_f32_16x16x32_bf16 v[22:25], v[176:179], v[228:231], v[22:25]
	v_mfma_f32_16x16x32_bf16 v[18:21], v[184:187], v[228:231], v[18:21]
	v_mfma_f32_16x16x32_bf16 v[6:9], v[176:179], v[236:239], v[6:9]
	v_mfma_f32_16x16x32_bf16 v[2:5], v[184:187], v[236:239], v[2:5]
	s_setprio 1
	s_barrier
	s_add_u32 s4, s4, 0x100
	s_addc_u32 s5, s5, 0
	s_add_u32 s24, s24, 0x100
	s_addc_u32 s25, s25, 0
	s_cmp_ge_u32 s43, s36
	s_mov_b32 s6, s43
	s_cbranch_scc0 .LBB0_404
	s_and_b64 vcc, exec, s[16:17]
	s_cbranch_vccz .LBB0_407
	s_barrier
